# conv stores without nt on top of relaxed unit-boundary waits and pipelined FoX LDS reads
# speedup vs baseline: 1.0041x; 1.0041x over previous
; #define LAS __attribute__((address_space(3)))
; #define ATT_DMA(jt, slot) do { glds16(ksrc + (size_t)(jt) * 64 * D, (unsigned)__builtin_amdgcn_readfirstlane(lds0 + A_K + (slot) * 8192 + wid * 1024)); \
;                                glds16(vsrc + (size_t)(jt) * 64 * D, (unsigned)__builtin_amdgcn_readfirstlane(lds0 + A_V + (slot) * 8192 + wid * 1024)); } while (0)
; __device__ __forceinline__ void conv_load(ConvRegs& c, const Args& a, size_t rowq, int col, int lane) {
; #pragma unroll
;     for (int i = 0; i < 4; ++i) { const size_t grow = rowq + i * 8 + (lane >> 3);
;         c.k[i] = *(const u32x4*)((const bf16*)(a.ws + WS_K) + grow * D + col + (lane & 7) * 8); c.v[i] = *(const u32x4*)((const bf16*)(a.ws + WS_V) + grow * D + col + (lane & 7) * 8); }
; __device__ __forceinline__ void prompt_unit_sb(const Args& a, int l, int b, int h, int qb, LAS unsigned char* lds) {
;     ...
;     f16x8 T00, T01; make_tri(T00, T01, r32, hi);
;     const int q0 = qb * 256, jb = q0 / 64, jd = jb + (wid >> 1);
;     const int col = W + h * HD;
;     const size_t rowb = (size_t)b * T;
;     const bf16* Kh = (const bf16*)(a.ws + WS_K) + rowb * D + col; const bf16* Vh = (const bf16*)(a.ws + WS_V) + rowb * D + col;
;     const unsigned lds0 = (unsigned)(uintptr_t)lds;
;     const bf16* ksrc = Kh + (size_t)lane * D + wid * 8;
;     const bf16* vsrc = Vh + (size_t)(16 * (wid & 3) + (lane >> 2)) * D + (wid >> 2) * 32 + (lane & 3) * 8;
;     ...
;     ATT_DMA(jb + 3); ATT_DMA(jb + 2); ATT_DMA(jb + 1); ATT_DMA(jb);
;     if (jb >= 4) { ATT_DMA(jb - 1); ATT_DMA(jb - 2); ATT_DMA(jb - 3); }
;     bf16x8 qr[4];
;     { const bf16* Qw = (const bf16*)(a.ws + WS_Q) + (rowb + q0 + wid * 32 + r32) * D + col;
; #pragma unroll
;       for (int d0 = 0; d0 < 4; ++d0) qr[d0] = *(const bf16x8*)(Qw + d0 * 16 + hi * 8); }
;     const lds_cptr vp0 = (lds_cptr)lds + B_V + ((lane >> 4) & 1) * 32 + (lane & 3) * 8 + (4 * hi + ((lane & 15) >> 2)) * 64;
;     const int qlim = 32 * (wid & 1) + r32;
;     LAS float* wsf = (LAS float*)(lds + B_WSF) + wid * 64;
;     LAS unsigned* flags = (LAS unsigned*)(lds + B_FLAG);
;     FoxState st; st.m = 0.f; st.l = 0.f; st.mq = (bf16x8){}; st.o[0] = (f32x16){}; st.o[1] = (f32x16){};
;     float R = 0.f; bool done = false;
;     { ConvRegs cv; conv_load(cv, a, rowb + q0 + wid * 32, col, lane); conv_store<1>(cv, a, l, h, rowb + q0 + wid * 32, lane); }
.LBB0_267:
	s_lshl_b32 s0, s4, 8
	s_ashr_i32 s4, s6, 7
	s_ashr_i32 s1, s0, 31
	v_lshrrev_b32_e32 v54, 5, v2
	s_add_u32 s0, s0, s7
	v_and_b32_e32 v169, 31, v19
	v_lshlrev_b32_e32 v55, 2, v54
	s_addc_u32 s1, s1, 0
	s_lshl_b32 s6, s82, 5
	v_cmp_lt_u32_e32 vcc, v55, v169
	v_or_b32_e32 v56, 16, v55
	s_ashr_i32 s7, s6, 31
	v_cndmask_b32_e64 v14, v181, 0, vcc
	v_cmp_lt_u32_e32 vcc, v56, v169
	v_or_b32_e32 v58, 1, v55
	s_add_u32 s78, s0, s6
	v_cndmask_b32_e64 v26, v181, 0, vcc
	v_or_b32_e32 v57, 2, v55
	v_cmp_lt_u32_e32 vcc, v58, v169
	s_addc_u32 s79, s1, s7
	v_or_b32_e32 v60, 17, v55
	v_cndmask_b32_e64 v15, v181, 0, vcc
	v_cmp_lt_u32_e32 vcc, v57, v169
	v_or_b32_e32 v160, s78, v169
	v_mov_b32_e32 v161, s79
	v_readlane_b32 s0, v242, 22
	v_cndmask_b32_e64 v16, v181, 0, vcc
	v_or_b32_e32 v59, 18, v55
	v_cmp_lt_u32_e32 vcc, v60, v169
	v_lshlrev_b64 v[6:7], 11, v[160:161]
	v_readlane_b32 s1, v242, 23
	v_cndmask_b32_e64 v27, v181, 0, vcc
	v_cmp_lt_u32_e32 vcc, v59, v169
	v_or_b32_e32 v62, 3, v55
	v_lshl_add_u64 v[6:7], s[0:1], 0, v[6:7]
	s_lshl_b32 s0, s5, 1
	s_mov_b32 s1, s87
	v_lshrrev_b32_e32 v1, 3, v2
	v_cndmask_b32_e64 v20, v181, 0, vcc
	v_or_b32_e32 v61, 8, v55
	v_cmp_lt_u32_e32 vcc, v62, v169
	v_lshl_add_u64 v[6:7], v[6:7], 0, s[0:1]
	v_lshlrev_b32_e32 v4, 4, v54
	v_or_b32_e32 v160, s78, v1
	v_cndmask_b32_e64 v17, v181, 0, vcc
	v_cmp_lt_u32_e32 vcc, v61, v169
	v_or_b32_e32 v64, 19, v55
	v_lshl_add_u64 v[24:25], v[6:7], 0, v[4:5]
	v_lshlrev_b32_e32 v4, 3, v2
	v_lshlrev_b64 v[166:167], 11, v[160:161]
	v_readlane_b32 s8, v242, 20
	v_cndmask_b32_e64 v21, v181, 0, vcc
	v_or_b32_e32 v63, 24, v55
	v_cmp_lt_u32_e32 vcc, v64, v169
	v_and_b32_e32 v168, 56, v4
	v_lshl_add_u64 v[6:7], s[94:95], 0, v[166:167]
	v_readlane_b32 s9, v242, 21
	v_cndmask_b32_e64 v22, v181, 0, vcc
	v_cmp_lt_u32_e32 vcc, v63, v169
	v_or_b32_e32 v65, 10, v55
	v_lshl_add_u64 v[6:7], v[6:7], 0, s[0:1]
	v_lshlrev_b32_e32 v4, 1, v168
	v_lshl_add_u64 v[10:11], s[8:9], 0, v[166:167]
	v_cndmask_b32_e64 v23, v181, 0, vcc
	v_or_b32_e32 v66, 9, v55
	v_lshl_add_u64 v[6:7], v[6:7], 0, v[4:5]
	v_cmp_lt_u32_e32 vcc, v65, v169
	v_lshl_add_u64 v[10:11], v[10:11], 0, s[0:1]
	global_load_dwordx4 v[6:9], v[6:7], off offset:1024
	v_cndmask_b32_e64 v28, v181, 0, vcc
	v_cmp_lt_u32_e32 vcc, v66, v169
	v_or_b32_e32 v67, 26, v55
	v_lshl_add_u64 v[10:11], v[10:11], 0, v[4:5]
	v_cndmask_b32_e64 v29, v181, 0, vcc
	v_or_b32_e32 v68, 25, v55
	global_load_dwordx4 v[10:13], v[10:11], off offset:1024
	v_cmp_lt_u32_e32 vcc, v67, v169
	v_or_b32_e32 v69, 11, v55
	v_or_b32_e32 v44, 0x4000, v166
	v_cndmask_b32_e64 v30, v181, 0, vcc
	v_cmp_lt_u32_e32 vcc, v68, v169
	v_mov_b32_e32 v45, v167
	v_or_b32_e32 v70, 27, v55
	v_cndmask_b32_e64 v31, v181, 0, vcc
	v_cmp_lt_u32_e32 vcc, v69, v169
	v_pack_b32_f16 v116, v14, v15
	v_lshl_add_u64 v[14:15], s[94:95], 0, v[44:45]
	v_cndmask_b32_e64 v32, v181, 0, vcc
	v_cmp_lt_u32_e32 vcc, v70, v169
	v_pack_b32_f16 v118, v21, v29
	v_lshl_add_u64 v[14:15], v[14:15], 0, s[0:1]
	v_cndmask_b32_e64 v21, v181, 0, vcc
	v_lshl_add_u64 v[14:15], v[14:15], 0, v[4:5]
	v_pack_b32_f16 v121, v20, v22
	v_pack_b32_f16 v123, v30, v21
	v_lshl_add_u64 v[20:21], s[8:9], 0, v[44:45]
	v_pack_b32_f16 v117, v16, v17
	global_load_dwordx4 v[14:17], v[14:15], off offset:1024
	v_lshl_add_u64 v[20:21], v[20:21], 0, s[0:1]
	v_lshl_add_u64 v[20:21], v[20:21], 0, v[4:5]
	v_pack_b32_f16 v122, v23, v31
	global_load_dwordx4 v[20:23], v[20:21], off offset:1024
	s_nop 0
	global_load_dwordx4 v[124:127], v[24:25], off offset:1024
	global_load_dwordx4 v[128:131], v[24:25], off offset:1056
	global_load_dwordx4 v[132:135], v[24:25], off offset:1088
	global_load_dwordx4 v[136:139], v[24:25], off offset:1120
	v_lshlrev_b32_e32 v24, 1, v19
	v_and_b32_e32 v24, 32, v24
	s_add_i32 s7, 0, 0x10000
	v_or_b32_e32 v46, 0x8000, v166
	v_mov_b32_e32 v47, v167
	v_add3_u32 v3, s7, v24, v3
	v_lshl_add_u64 v[24:25], s[94:95], 0, v[46:47]
	v_lshlrev_b32_e32 v29, 4, v19
	v_pack_b32_f16 v119, v28, v32
	v_lshlrev_b32_e32 v28, 8, v54
	v_lshl_add_u64 v[24:25], v[24:25], 0, s[0:1]
	v_and_b32_e32 v29, 0xc0, v29
	v_lshl_add_u64 v[24:25], v[24:25], 0, v[4:5]
	v_add3_u32 v170, v3, v28, v29
	v_lshl_add_u64 v[28:29], s[8:9], 0, v[46:47]
	v_pack_b32_f16 v120, v26, v27
	global_load_dwordx4 v[24:27], v[24:25], off offset:1024
	v_lshl_add_u64 v[28:29], v[28:29], 0, s[0:1]
	v_lshl_add_u64 v[28:29], v[28:29], 0, v[4:5]
	global_load_dwordx4 v[28:31], v[28:29], off offset:1024
	v_or_b32_e32 v48, 0xc000, v166
	v_mov_b32_e32 v49, v167
	v_lshl_add_u64 v[32:33], s[94:95], 0, v[48:49]
	v_lshl_add_u64 v[34:35], s[8:9], 0, v[48:49]
	v_lshl_add_u64 v[32:33], v[32:33], 0, s[0:1]
	v_lshl_add_u64 v[34:35], v[34:35], 0, s[0:1]
	v_lshl_add_u64 v[32:33], v[32:33], 0, v[4:5]
	v_lshl_add_u64 v[36:37], v[34:35], 0, v[4:5]
	global_load_dwordx4 v[32:35], v[32:33], off offset:1024
	s_nop 0
	global_load_dwordx4 v[36:39], v[36:37], off offset:1024
	v_and_or_b32 v3, s6, 32, v169
	v_readlane_b32 s6, v242, 24
	v_readlane_b32 s7, v242, 25
	s_lshl_b32 s92, s5, 2
	s_mov_b32 s93, s87
	v_lshl_add_u64 v[40:41], s[6:7], 0, v[166:167]
	v_readlane_b32 s8, v242, 26
	v_lshl_add_u64 v[40:41], v[40:41], 0, s[92:93]
	v_lshlrev_b32_e32 v4, 2, v168
	v_readlane_b32 s9, v242, 27
	v_lshl_add_u64 v[50:51], v[40:41], 0, v[4:5]
	v_lshlrev_b32_e32 v171, 10, v54
	v_lshl_add_u64 v[40:41], s[8:9], 0, v[166:167]
	v_lshl_add_u64 v[40:41], v[40:41], 0, s[92:93]
	v_lshl_add_u64 v[52:53], v[40:41], 0, v[4:5]
	s_lshl_b32 s1, s82, 2
	s_waitcnt vmcnt(0)
; #define LAS __attribute__((address_space(3)))
; __device__ __forceinline__ float bflo(unsigned w) { return __uint_as_float(w << 16); }
; __device__ __forceinline__ float bfhi(unsigned w) { return __uint_as_float(w & 0xffff0000u); }
; #define ATT_WAIT_BAR_N(N) asm volatile("s_waitcnt vmcnt(" #N ") lgkmcnt(0)\n\ts_barrier" ::: "memory")
; template <int TYPE>
; __device__ __forceinline__ void conv_store(const ConvRegs& c, const Args& a, int l, int h, size_t rowq, int lane) {
; #pragma unroll
;     for (int i = 0; i < 4; ++i) { const size_t grow = rowq + i * 8 + (lane >> 3);
;         float* ko = a.out + (TYPE == 0 ? O_FKP : O_SKP) + ((size_t)l * MP + grow) * W + h * HD + (lane & 7) * 8;
;         float* vo = a.out + (TYPE == 0 ? O_FVP : O_SVP) + ((size_t)l * MP + grow) * W + h * HD + (lane & 7) * 8;
;         const u32x4 kw = c.k[i], vw = c.v[i];
;         __builtin_nontemporal_store((f32x4){bflo(kw.x), bfhi(kw.x), bflo(kw.y), bfhi(kw.y)}, (f32x4*)ko); __builtin_nontemporal_store((f32x4){bflo(kw.z), bfhi(kw.z), bflo(kw.w), bfhi(kw.w)}, (f32x4*)(ko + 4));
;         __builtin_nontemporal_store((f32x4){bflo(vw.x), bfhi(vw.x), bflo(vw.y), bfhi(vw.y)}, (f32x4*)vo); __builtin_nontemporal_store((f32x4){bflo(vw.z), bfhi(vw.z), bflo(vw.w), bfhi(vw.w)}, (f32x4*)(vo + 4)); }
; }
; __device__ __forceinline__ void prompt_unit_sb(const Args& a, int l, int b, int h, int qb, LAS unsigned char* lds) {
;     ...
;     const lds_cptr vp0 = (lds_cptr)lds + B_V + ((lane >> 4) & 1) * 32 + (lane & 3) * 8 + (4 * hi + ((lane & 15) >> 2)) * 64;
;     const int qlim = 32 * (wid & 1) + r32;
;     LAS float* wsf = (LAS float*)(lds + B_WSF) + wid * 64;
;     LAS unsigned* flags = (LAS unsigned*)(lds + B_FLAG);
;     FoxState st; st.m = 0.f; st.l = 0.f; st.mq = (bf16x8){}; st.o[0] = (f32x16){}; st.o[1] = (f32x16){};
;     float R = 0.f; bool done = false;
;     { ConvRegs cv; conv_load(cv, a, rowb + q0 + wid * 32, col, lane); conv_store<1>(cv, a, l, h, rowb + q0 + wid * 32, lane); }
;     for (int it = 0; ; ++it) {
;         const int need = jb - it;
;         if (need >= 3) ATT_WAIT_BAR_N(6); else if (need == 2) ATT_WAIT_BAR_N(4); else if (need == 1) ATT_WAIT_BAR_N(2); else ATT_WAIT_BAR_N(0);
	v_lshlrev_b32_e32 v40, 16, v6
	v_and_b32_e32 v41, 0xffff0000, v6
	v_lshlrev_b32_e32 v42, 16, v7
	v_and_b32_e32 v43, 0xffff0000, v7
	v_lshlrev_b32_e32 v6, 16, v8
	v_and_b32_e32 v7, 0xffff0000, v8
	v_lshlrev_b32_e32 v8, 16, v9
	v_and_b32_e32 v9, 0xffff0000, v9
	global_store_dwordx4 v[50:51], v[6:9], off offset:16
	global_store_dwordx4 v[50:51], v[40:43], off
	s_add_i32 s1, s1, 0
	v_lshlrev_b32_e32 v6, 16, v10
	v_and_b32_e32 v7, 0xffff0000, v10
	v_lshlrev_b32_e32 v8, 16, v11
	v_and_b32_e32 v9, 0xffff0000, v11
	global_store_dwordx4 v[52:53], v[6:9], off
	v_cmp_lt_u32_e64 s[10:11], v58, v3
	v_cmp_lt_u32_e64 s[14:15], v57, v3
	v_lshlrev_b32_e32 v6, 16, v12
	v_and_b32_e32 v7, 0xffff0000, v12
	v_lshlrev_b32_e32 v8, 16, v13
	v_and_b32_e32 v9, 0xffff0000, v13
	global_store_dwordx4 v[52:53], v[6:9], off offset:16
	v_cmp_lt_u32_e64 s[18:19], v62, v3
	v_cmp_lt_u32_e64 s[22:23], v61, v3
	v_lshl_add_u64 v[6:7], s[6:7], 0, v[44:45]
	v_lshl_add_u64 v[6:7], v[6:7], 0, s[92:93]
	v_lshl_add_u64 v[10:11], v[6:7], 0, v[4:5]
	v_lshl_add_u64 v[6:7], s[8:9], 0, v[44:45]
	v_lshl_add_u64 v[6:7], v[6:7], 0, s[92:93]
	v_lshl_add_u64 v[12:13], v[6:7], 0, v[4:5]
	v_lshlrev_b32_e32 v6, 16, v14
	v_and_b32_e32 v7, 0xffff0000, v14
	v_lshlrev_b32_e32 v8, 16, v15
	v_and_b32_e32 v9, 0xffff0000, v15
	global_store_dwordx4 v[10:11], v[6:9], off
	v_cmp_lt_u32_e64 s[26:27], v66, v3
	v_cmp_lt_u32_e64 s[30:31], v65, v3
	v_lshlrev_b32_e32 v6, 16, v16
	v_and_b32_e32 v7, 0xffff0000, v16
	v_lshlrev_b32_e32 v8, 16, v17
	v_and_b32_e32 v9, 0xffff0000, v17
	global_store_dwordx4 v[10:11], v[6:9], off offset:16
	v_mov_b32_e32 v16, v5
	v_mov_b32_e32 v17, v5
	v_lshlrev_b32_e32 v6, 16, v20
	v_and_b32_e32 v7, 0xffff0000, v20
	v_lshlrev_b32_e32 v8, 16, v21
	v_and_b32_e32 v9, 0xffff0000, v21
	global_store_dwordx4 v[12:13], v[6:9], off
	v_and_or_b32 v20, v183, 64, v169
	v_cmp_lt_u32_e64 s[36:37], v69, v3
	v_lshlrev_b32_e32 v6, 16, v22
	v_and_b32_e32 v7, 0xffff0000, v22
	v_lshlrev_b32_e32 v8, 16, v23
	v_and_b32_e32 v9, 0xffff0000, v23
	global_store_dwordx4 v[12:13], v[6:9], off offset:16
	v_cmp_lt_u32_e64 s[40:41], v56, v3
	v_cmp_lt_u32_e64 s[44:45], v60, v3
	v_lshl_add_u64 v[6:7], s[6:7], 0, v[46:47]
	v_lshl_add_u64 v[6:7], v[6:7], 0, s[92:93]
	v_lshl_add_u64 v[10:11], v[6:7], 0, v[4:5]
	v_lshl_add_u64 v[6:7], s[8:9], 0, v[46:47]
	v_lshl_add_u64 v[6:7], v[6:7], 0, s[92:93]
	v_lshl_add_u64 v[12:13], v[6:7], 0, v[4:5]
	v_lshlrev_b32_e32 v6, 16, v24
	v_and_b32_e32 v7, 0xffff0000, v24
	v_lshlrev_b32_e32 v8, 16, v25
	v_and_b32_e32 v9, 0xffff0000, v25
	global_store_dwordx4 v[10:11], v[6:9], off
	v_cmp_lt_u32_e64 s[48:49], v59, v3
	v_cmp_lt_u32_e64 s[52:53], v64, v3
	v_lshlrev_b32_e32 v6, 16, v26
	v_and_b32_e32 v7, 0xffff0000, v26
	v_lshlrev_b32_e32 v8, 16, v27
	v_and_b32_e32 v9, 0xffff0000, v27
	global_store_dwordx4 v[10:11], v[6:9], off offset:16
	v_cmp_lt_u32_e64 s[56:57], v63, v3
	v_cmp_lt_u32_e64 s[60:61], v68, v3
	v_lshlrev_b32_e32 v6, 16, v28
	v_and_b32_e32 v7, 0xffff0000, v28
	v_lshlrev_b32_e32 v8, 16, v29
	v_and_b32_e32 v9, 0xffff0000, v29
	global_store_dwordx4 v[12:13], v[6:9], off
	v_cmp_lt_u32_e64 s[64:65], v67, v3
	v_cmp_lt_u32_e64 s[68:69], v70, v3
	v_lshlrev_b32_e32 v6, 16, v30
	v_and_b32_e32 v7, 0xffff0000, v30
	v_lshlrev_b32_e32 v8, 16, v31
	v_and_b32_e32 v9, 0xffff0000, v31
	global_store_dwordx4 v[12:13], v[6:9], off offset:16
	v_cmp_eq_u32_e64 s[72:73], 0, v2
	s_lshl_b32 s5, s3, 15
	v_lshl_add_u64 v[6:7], s[6:7], 0, v[48:49]
	v_lshl_add_u64 v[6:7], v[6:7], 0, s[92:93]
	v_lshl_add_u64 v[10:11], v[6:7], 0, v[4:5]
	v_lshl_add_u64 v[6:7], s[8:9], 0, v[48:49]
	v_lshl_add_u64 v[6:7], v[6:7], 0, s[92:93]
	v_lshl_add_u64 v[12:13], v[6:7], 0, v[4:5]
	v_lshlrev_b32_e32 v4, 4, v169
	v_add3_u32 v172, 0, v171, v4
	v_or_b32_e32 v4, 32, v55
	v_cmp_lt_u32_e64 s[8:9], v4, v3
	v_or_b32_e32 v4, 33, v55
	v_cmp_lt_u32_e64 s[12:13], v4, v3
	v_or_b32_e32 v4, 34, v55
	v_cmp_lt_u32_e64 s[16:17], v4, v3
	v_or_b32_e32 v4, 35, v55
	v_cmp_lt_u32_e64 s[20:21], v4, v3
	v_or_b32_e32 v4, 40, v55
	v_cmp_lt_u32_e64 s[24:25], v4, v3
	v_or_b32_e32 v4, 41, v55
	v_cmp_lt_u32_e64 s[28:29], v4, v3
	v_or_b32_e32 v4, 42, v55
	v_cmp_lt_u32_e64 s[34:35], v4, v3
	v_or_b32_e32 v4, 43, v55
	v_cmp_lt_u32_e64 s[38:39], v4, v3
	v_or_b32_e32 v4, 48, v55
	v_cmp_lt_u32_e64 s[42:43], v4, v3
	v_or_b32_e32 v4, 49, v55
	v_cmp_lt_u32_e64 s[46:47], v4, v3
	v_or_b32_e32 v4, 50, v55
	v_cmp_lt_u32_e64 s[50:51], v4, v3
	v_or_b32_e32 v4, 51, v55
	v_lshlrev_b32_e32 v6, 16, v32
	v_and_b32_e32 v7, 0xffff0000, v32
	v_lshlrev_b32_e32 v8, 16, v33
	v_and_b32_e32 v9, 0xffff0000, v33
	v_cmp_lt_u32_e64 s[54:55], v4, v3
	v_or_b32_e32 v4, 56, v55
	global_store_dwordx4 v[10:11], v[6:9], off
	v_cmp_lt_u32_e64 s[58:59], v4, v3
	v_or_b32_e32 v4, 57, v55
	v_lshlrev_b32_e32 v6, 16, v34
	v_and_b32_e32 v7, 0xffff0000, v34
	v_lshlrev_b32_e32 v8, 16, v35
	v_and_b32_e32 v9, 0xffff0000, v35
	global_store_dwordx4 v[10:11], v[6:9], off offset:16
	v_cmp_lt_u32_e64 s[62:63], v4, v3
	v_or_b32_e32 v4, 58, v55
	v_lshlrev_b32_e32 v6, 16, v36
	v_and_b32_e32 v7, 0xffff0000, v36
	v_lshlrev_b32_e32 v8, 16, v37
	v_and_b32_e32 v9, 0xffff0000, v37
	global_store_dwordx4 v[12:13], v[6:9], off
	v_cmp_lt_u32_e64 s[66:67], v4, v3
	v_or_b32_e32 v4, 59, v55
	v_lshlrev_b32_e32 v6, 16, v38
	v_and_b32_e32 v7, 0xffff0000, v38
	v_lshlrev_b32_e32 v8, 16, v39
	v_and_b32_e32 v9, 0xffff0000, v39
	global_store_dwordx4 v[12:13], v[6:9], off offset:16
	v_cmp_lt_u32_e64 s[6:7], v55, v3
	v_cmp_lt_u32_e64 s[70:71], v4, v3
	s_lshl_b32 s3, s3, 2
	v_mov_b32_e32 v2, v5
	v_mov_b32_e32 v3, v5
	v_mov_b32_e32 v4, v5
	v_mov_b32_e32 v6, v5
	v_mov_b32_e32 v7, v5
	v_mov_b32_e32 v8, v5
	v_mov_b32_e32 v9, v5
	v_mov_b32_e32 v10, v5
	v_mov_b32_e32 v11, v5
	v_mov_b32_e32 v12, v5
	v_mov_b32_e32 v13, v5
	v_mov_b32_e32 v14, v5
	v_mov_b32_e32 v15, v5
	v_lshlrev_b32_e32 v173, 2, v20
	v_mov_b64_e32 v[34:35], v[16:17]
	v_mov_b64_e32 v[50:51], v[16:17]
	s_add_i32 s1, s1, 0x20c00
	s_mov_b32 s85, 0
	s_lshl_b32 s93, s4, 13
	s_sub_i32 s94, 0x30000, s5
	s_sub_i32 s95, s4, s3
	s_sub_i32 s33, 0, s3
	v_mov_b32_e32 v52, 0
	s_mov_b64 s[74:75], 0
	v_mov_b64_e32 v[32:33], v[14:15]
	v_mov_b64_e32 v[30:31], v[12:13]
	v_mov_b64_e32 v[28:29], v[10:11]
	v_mov_b64_e32 v[26:27], v[8:9]
	v_mov_b64_e32 v[24:25], v[6:7]
	v_mov_b64_e32 v[22:23], v[4:5]
	v_mov_b64_e32 v[20:21], v[2:3]
	v_mov_b64_e32 v[48:49], v[14:15]
	v_mov_b64_e32 v[46:47], v[12:13]
	v_mov_b64_e32 v[44:45], v[10:11]
	v_mov_b64_e32 v[42:43], v[8:9]
	v_mov_b64_e32 v[40:41], v[6:7]
	v_mov_b64_e32 v[38:39], v[4:5]
	v_mov_b64_e32 v[36:37], v[2:3]
	s_mov_b32 s3, 28
	s_add_i32 s89, s33, s3
	s_waitcnt lgkmcnt(0)
	s_barrier
	s_branch .LBB0_281

; #define LAS __attribute__((address_space(3)))
; __device__ __forceinline__ void conv_load(ConvRegs& c, const Args& a, size_t rowq, int col, int lane) {
; #pragma unroll
;     for (int i = 0; i < 4; ++i) { const size_t grow = rowq + i * 8 + (lane >> 3);
; __device__ __forceinline__ void prompt_unit_fox(const Args& a, int l, int b, int h, int qb, LAS unsigned char* lds) {
;     int tid_ = threadIdx.x; asm volatile("" : "+v"(tid_));
;     const int tid = tid_, lane = tid & 63, r32 = lane & 31, hi = lane >> 5, wid = __builtin_amdgcn_readfirstlane(tid >> 6);
;     const int q0 = qb * 256, NP = (q0 + 256) / 128, jd = q0 / 64 + (wid >> 1), jpd = jd >> 1;
;     const bool lateB = wid >= 4;
;     const int col = h * HD;
;     const size_t rowb = (size_t)b * T;
;     const bf16* Kh = (const bf16*)(a.ws + WS_K) + rowb * D + col; const bf16* Vh = (const bf16*)(a.ws + WS_V) + rowb * D + col;
;     const unsigned lds0 = (unsigned)(uintptr_t)lds;
;     const bf16* ksrc = Kh + (size_t)lane * D + wid * 8;
;     const bf16* vsrc = Vh + (size_t)(16 * (wid & 3) + (lane >> 2)) * D + (wid >> 2) * 32 + (lane & 3) * 8;
;     ...
;     ATT_DMA2(NP - 1, 0);
;     { const int idx = tid * 4; if (idx < q0 + 256) { const f32x4 c = *(const f32x4*)((const float*)(a.ws + WS_CKP) + (size_t)(b * 8 + h) * T + idx); *(LAS f32x4*)(lds + F_CK + idx * 4) = c;
; #pragma unroll
;         for (int e = 0; e < 4; ++e) { const float h1 = bf_hi_part(c[e]), r1 = c[e] - h1, h2 = bf_hi_part(r1), r2 = r1 - h2; ((LAS u32x2*)(lds + F_AUG))[idx + e] = (u32x2){cvtpk(h1, h2), cvtpk(r2, -1.0f)}; } } }
;     bf16x8 qr[4];
;     { const bf16* Qw = (const bf16*)(a.ws + WS_Q) + (rowb + q0 + wid * 32 + r32) * D + col;
; #pragma unroll
;       for (int d0 = 0; d0 < 4; ++d0) qr[d0] = *(const bf16x8*)(Qw + d0 * 16 + hi * 8); }
;     const lds_cptr vp0 = (lds_cptr)lds + F_V + ((lane >> 4) & 1) * 32 + (lane & 3) * 8 + (4 * hi + ((lane & 15) >> 2)) * 64;
;     const int ql = 32 * (wid & 1) + r32, qlim = ql + 1;
;     LAS float* wsf = (LAS float*)(lds + F_WSF) + wid * 64;
;     FoxState st; st.m = 0.f; st.l = 0.f; st.mq = (bf16x8){}; st.o[0] = (f32x16){}; st.o[1] = (f32x16){};
;     PairP pp; bool pending = false;
; #pragma unroll
;     for (int i = 0; i < 8; ++i) pp.w[i] = (u32x4){0u, 0u, 0u, 0u};
;     { ConvRegs cv; conv_load(cv, a, rowb + q0 + wid * 32, col, lane); conv_store<0>(cv, a, l, h, rowb + q0 + wid * 32, lane); }
.LBB0_311:
	s_or_b64 exec, exec, s[0:1]
	s_lshl_b32 s0, s6, 2
	s_ashr_i32 s1, s3, 7
	s_add_i32 s1, s1, s0
	s_ashr_i32 s89, s1, 1
	s_cmp_lt_i32 s77, 4
	s_cselect_b64 s[92:93], -1, 0
	s_lshl_b32 s0, s5, 11
	s_lshl_b32 s5, s77, 5
	s_or_b32 s0, s7, s0
	s_ashr_i32 s1, s5, 31
	s_add_u32 s91, s5, s0
	v_and_b32_e32 v175, 31, v19
	s_addc_u32 s0, s1, 0
	v_or_b32_e32 v168, s91, v175
	v_mov_b32_e32 v169, s0
	v_lshrrev_b32_e32 v1, 3, v20
	v_lshlrev_b64 v[2:3], 11, v[168:169]
	v_or_b32_e32 v168, s91, v1
	v_lshlrev_b32_e32 v4, 3, v20
	v_lshlrev_b64 v[170:171], 11, v[168:169]
	s_lshl_b32 s74, s4, 1
	s_mov_b32 s75, s87
	v_and_b32_e32 v174, 56, v4
	v_lshl_add_u64 v[8:9], s[94:95], 0, v[170:171]
	v_lshl_add_u64 v[8:9], v[8:9], 0, s[74:75]
	v_lshlrev_b32_e32 v4, 1, v174
	v_readlane_b32 s6, v242, 20
	v_lshl_add_u64 v[8:9], v[8:9], 0, v[4:5]
	v_readlane_b32 s7, v242, 21
	global_load_dwordx4 v[22:25], v[8:9], off
	v_or_b32_e32 v58, 0x4000, v170
	v_lshl_add_u64 v[8:9], s[6:7], 0, v[170:171]
	v_lshl_add_u64 v[8:9], v[8:9], 0, s[74:75]
	v_lshl_add_u64 v[8:9], v[8:9], 0, v[4:5]
	v_mov_b32_e32 v59, v171
	global_load_dwordx4 v[26:29], v[8:9], off
	v_lshl_add_u64 v[8:9], s[94:95], 0, v[58:59]
	v_lshl_add_u64 v[8:9], v[8:9], 0, s[74:75]
	v_lshl_add_u64 v[8:9], v[8:9], 0, v[4:5]
	global_load_dwordx4 v[30:33], v[8:9], off
	v_lshl_add_u64 v[8:9], s[6:7], 0, v[58:59]
	v_lshrrev_b32_e32 v21, 5, v20
	v_lshl_add_u64 v[8:9], v[8:9], 0, s[74:75]
	v_lshlrev_b32_e32 v7, 1, v19
	v_lshrrev_b32_e32 v10, 2, v19
	v_lshlrev_b32_e32 v66, 2, v21
	v_lshl_add_u64 v[8:9], v[8:9], 0, v[4:5]
	v_and_b32_e32 v7, 32, v7
	global_load_dwordx4 v[34:37], v[8:9], off
	v_and_or_b32 v8, v10, 3, v66
	v_add_u32_e32 v7, 0, v7
	v_lshlrev_b32_e32 v8, 6, v8
	v_or_b32_e32 v60, 0x8000, v170
	v_mov_b32_e32 v61, v171
	v_add3_u32 v180, v7, v6, v8
	v_lshl_add_u64 v[6:7], s[94:95], 0, v[60:61]
	v_and_or_b32 v67, s5, 32, v175
	s_and_b32 s5, s3, 0x3fffffc0
	v_lshl_add_u64 v[6:7], v[6:7], 0, s[74:75]
	v_writelane_b32 v237, s0, 11
	s_lshl_b32 s0, s4, 2
	s_lshl_b32 s4, s5, 2
	v_lshl_add_u64 v[6:7], v[6:7], 0, v[4:5]
	v_lshl_add_u64 v[10:11], s[6:7], 0, v[60:61]
	s_add_i32 s78, s4, 0
	v_readlane_b32 s4, v242, 22
	global_load_dwordx4 v[38:41], v[6:7], off
	v_lshl_add_u64 v[10:11], v[10:11], 0, s[74:75]
	v_readlane_b32 s5, v242, 23
	v_lshl_add_u64 v[10:11], v[10:11], 0, v[4:5]
	v_readlane_b32 s8, v242, 45
	v_lshl_add_u64 v[2:3], s[4:5], 0, v[2:3]
	v_readlane_b32 s4, v242, 43
	global_load_dwordx4 v[42:45], v[10:11], off
	v_mov_b32_e32 v173, v5
	v_lshlrev_b32_e32 v172, 4, v21
	v_lshl_add_u64 v[2:3], v[2:3], 0, s[74:75]
	v_or_b32_e32 v62, 0xc000, v170
	v_mov_b32_e32 v63, v171
	v_readlane_b32 s5, v242, 44
	v_readlane_b32 s9, v242, 46
	s_mov_b32 s1, s87
	v_lshl_add_u64 v[6:7], s[4:5], 0, v[170:171]
	v_lshl_add_u64 v[8:9], s[8:9], 0, v[170:171]
	v_lshl_add_u64 v[2:3], v[2:3], 0, v[172:173]
	v_lshl_add_u64 v[46:47], s[94:95], 0, v[62:63]
	v_lshl_add_u64 v[48:49], s[6:7], 0, v[62:63]
	v_lshl_add_u64 v[54:55], v[6:7], 0, s[0:1]
	v_lshl_add_u64 v[56:57], v[8:9], 0, s[0:1]
	global_load_dwordx4 v[6:9], v[2:3], off
	global_load_dwordx4 v[10:13], v[2:3], off offset:32
	global_load_dwordx4 v[14:17], v[2:3], off offset:64
	global_load_dwordx4 v[116:119], v[2:3], off offset:96
	v_lshl_add_u64 v[2:3], v[46:47], 0, s[74:75]
	v_lshl_add_u64 v[46:47], v[48:49], 0, s[74:75]
	v_lshl_add_u64 v[2:3], v[2:3], 0, v[4:5]
	v_lshl_add_u64 v[50:51], v[46:47], 0, v[4:5]
	global_load_dwordx4 v[46:49], v[2:3], off
	s_nop 0
	global_load_dwordx4 v[50:53], v[50:51], off
	v_lshlrev_b32_e32 v4, 2, v174
	v_lshl_add_u64 v[2:3], v[54:55], 0, v[4:5]
	v_lshl_add_u64 v[64:65], v[56:57], 0, v[4:5]
	s_add_i32 s78, s78, 0x1a000
	v_cmp_lt_u32_e64 s[12:13], v66, v67
	v_cmp_gt_u32_e64 s[6:7], 32, v20
	v_lshlrev_b32_e32 v173, 10, v21
	v_lshlrev_b32_e32 v188, 4, v175
	v_cndmask_b32_e64 v122, 0, v185, s[6:7]
	v_cndmask_b32_e64 v121, 0, -1.0, s[6:7]
	v_mov_b32_e32 v120, v5
	v_mov_b32_e32 v123, v5
	v_lshl_add_u32 v182, v175, 2, s78
	v_mov_b32_e32 v156, v5
	s_waitcnt vmcnt(0)
	v_lshlrev_b32_e32 v54, 16, v22
	v_and_b32_e32 v55, 0xffff0000, v22
	v_lshlrev_b32_e32 v56, 16, v23
	v_and_b32_e32 v57, 0xffff0000, v23
	v_lshlrev_b32_e32 v22, 16, v24
	v_and_b32_e32 v23, 0xffff0000, v24
	v_lshlrev_b32_e32 v24, 16, v25
	v_and_b32_e32 v25, 0xffff0000, v25
	global_store_dwordx4 v[2:3], v[22:25], off offset:16
	global_store_dwordx4 v[2:3], v[54:57], off
	v_lshl_add_u64 v[2:3], s[4:5], 0, v[58:59]
	v_lshlrev_b32_e32 v22, 16, v26
	v_and_b32_e32 v23, 0xffff0000, v26
	v_lshlrev_b32_e32 v24, 16, v27
	v_and_b32_e32 v25, 0xffff0000, v27
	global_store_dwordx4 v[64:65], v[22:25], off
	v_lshl_add_u64 v[2:3], v[2:3], 0, s[0:1]
	v_lshl_add_u64 v[2:3], v[2:3], 0, v[4:5]
	v_lshlrev_b32_e32 v22, 16, v28
	v_and_b32_e32 v23, 0xffff0000, v28
	v_lshlrev_b32_e32 v24, 16, v29
	v_and_b32_e32 v25, 0xffff0000, v29
	global_store_dwordx4 v[64:65], v[22:25], off offset:16
	v_mov_b32_e32 v54, v5
	v_mov_b32_e32 v55, v5
	v_lshl_add_u64 v[22:23], s[8:9], 0, v[58:59]
	v_lshl_add_u64 v[22:23], v[22:23], 0, s[0:1]
	v_lshl_add_u64 v[26:27], v[22:23], 0, v[4:5]
	v_lshlrev_b32_e32 v22, 16, v30
	v_and_b32_e32 v23, 0xffff0000, v30
	v_lshlrev_b32_e32 v24, 16, v31
	v_and_b32_e32 v25, 0xffff0000, v31
	global_store_dwordx4 v[2:3], v[22:25], off
	v_mov_b32_e32 v56, v5
	v_mov_b32_e32 v57, v5
	v_lshlrev_b32_e32 v22, 16, v32
	v_and_b32_e32 v23, 0xffff0000, v32
	v_lshlrev_b32_e32 v24, 16, v33
	v_and_b32_e32 v25, 0xffff0000, v33
	global_store_dwordx4 v[2:3], v[22:25], off offset:16
	v_lshl_add_u64 v[2:3], s[4:5], 0, v[60:61]
	v_lshl_add_u64 v[2:3], v[2:3], 0, s[0:1]
	v_lshlrev_b32_e32 v22, 16, v34
	v_and_b32_e32 v23, 0xffff0000, v34
; #define LAS __attribute__((address_space(3)))
; __device__ __forceinline__ float bflo(unsigned w) { return __uint_as_float(w << 16); }
; __device__ __forceinline__ float bfhi(unsigned w) { return __uint_as_float(w & 0xffff0000u); }
; #define ATT_WAIT_BAR() asm volatile("s_waitcnt vmcnt(0) lgkmcnt(0)\n\ts_barrier" ::: "memory")
; template <int TYPE>
; __device__ __forceinline__ void conv_store(const ConvRegs& c, const Args& a, int l, int h, size_t rowq, int lane) {
; #pragma unroll
;     for (int i = 0; i < 4; ++i) { const size_t grow = rowq + i * 8 + (lane >> 3);
;         float* ko = a.out + (TYPE == 0 ? O_FKP : O_SKP) + ((size_t)l * MP + grow) * W + h * HD + (lane & 7) * 8;
;         float* vo = a.out + (TYPE == 0 ? O_FVP : O_SVP) + ((size_t)l * MP + grow) * W + h * HD + (lane & 7) * 8;
;         const u32x4 kw = c.k[i], vw = c.v[i];
;         __builtin_nontemporal_store((f32x4){bflo(kw.x), bfhi(kw.x), bflo(kw.y), bfhi(kw.y)}, (f32x4*)ko); __builtin_nontemporal_store((f32x4){bflo(kw.z), bfhi(kw.z), bflo(kw.w), bfhi(kw.w)}, (f32x4*)(ko + 4));
;         __builtin_nontemporal_store((f32x4){bflo(vw.x), bfhi(vw.x), bflo(vw.y), bfhi(vw.y)}, (f32x4*)vo); __builtin_nontemporal_store((f32x4){bflo(vw.z), bfhi(vw.z), bflo(vw.w), bfhi(vw.w)}, (f32x4*)(vo + 4)); }
; }
; __device__ __forceinline__ void prompt_unit_fox(const Args& a, int l, int b, int h, int qb, LAS unsigned char* lds) {
;     ...
;     const lds_cptr vp0 = (lds_cptr)lds + F_V + ((lane >> 4) & 1) * 32 + (lane & 3) * 8 + (4 * hi + ((lane & 15) >> 2)) * 64;
;     const int ql = 32 * (wid & 1) + r32, qlim = ql + 1;
;     LAS float* wsf = (LAS float*)(lds + F_WSF) + wid * 64;
;     FoxState st; st.m = 0.f; st.l = 0.f; st.mq = (bf16x8){}; st.o[0] = (f32x16){}; st.o[1] = (f32x16){};
;     PairP pp; bool pending = false;
; #pragma unroll
;     for (int i = 0; i < 8; ++i) pp.w[i] = (u32x4){0u, 0u, 0u, 0u};
;     { ConvRegs cv; conv_load(cv, a, rowb + q0 + wid * 32, col, lane); conv_store<0>(cv, a, l, h, rowb + q0 + wid * 32, lane); }
;     int slot = 0, pslot = 0;
;     ...
;         ATT_WAIT_BAR();
	v_lshlrev_b32_e32 v24, 16, v35
	v_and_b32_e32 v25, 0xffff0000, v35
	global_store_dwordx4 v[26:27], v[22:25], off
	v_lshl_add_u64 v[2:3], v[2:3], 0, v[4:5]
	v_mov_b32_e32 v58, v5
	v_lshlrev_b32_e32 v22, 16, v36
	v_and_b32_e32 v23, 0xffff0000, v36
	v_lshlrev_b32_e32 v24, 16, v37
	v_and_b32_e32 v25, 0xffff0000, v37
	global_store_dwordx4 v[26:27], v[22:25], off offset:16
	v_mov_b32_e32 v59, v5
	v_mov_b32_e32 v64, v5
	v_lshl_add_u64 v[22:23], s[8:9], 0, v[60:61]
	v_lshl_add_u64 v[22:23], v[22:23], 0, s[0:1]
	v_lshl_add_u64 v[26:27], v[22:23], 0, v[4:5]
	v_lshlrev_b32_e32 v22, 16, v38
	v_and_b32_e32 v23, 0xffff0000, v38
	v_lshlrev_b32_e32 v24, 16, v39
	v_and_b32_e32 v25, 0xffff0000, v39
	global_store_dwordx4 v[2:3], v[22:25], off
	v_mov_b32_e32 v60, v5
	v_mov_b32_e32 v61, v5
	v_lshlrev_b32_e32 v22, 16, v40
	v_and_b32_e32 v23, 0xffff0000, v40
	v_lshlrev_b32_e32 v24, 16, v41
	v_and_b32_e32 v25, 0xffff0000, v41
	global_store_dwordx4 v[2:3], v[22:25], off offset:16
	v_lshl_add_u64 v[2:3], s[4:5], 0, v[62:63]
	v_lshl_add_u64 v[2:3], v[2:3], 0, s[0:1]
	v_lshlrev_b32_e32 v22, 16, v42
	v_and_b32_e32 v23, 0xffff0000, v42
	v_lshlrev_b32_e32 v24, 16, v43
	v_and_b32_e32 v25, 0xffff0000, v43
	global_store_dwordx4 v[26:27], v[22:25], off
	v_lshl_add_u64 v[2:3], v[2:3], 0, v[4:5]
	v_mov_b32_e32 v65, v5
	v_lshlrev_b32_e32 v22, 16, v44
	v_and_b32_e32 v23, 0xffff0000, v44
	v_lshlrev_b32_e32 v24, 16, v45
	v_and_b32_e32 v25, 0xffff0000, v45
	global_store_dwordx4 v[26:27], v[22:25], off offset:16
	v_mov_b32_e32 v157, v5
	v_mov_b32_e32 v158, v5
	v_lshl_add_u64 v[22:23], s[8:9], 0, v[62:63]
	v_lshl_add_u64 v[22:23], v[22:23], 0, s[0:1]
	v_lshl_add_u64 v[26:27], v[22:23], 0, v[4:5]
	v_lshlrev_b32_e32 v22, 16, v46
	v_and_b32_e32 v23, 0xffff0000, v46
	v_lshlrev_b32_e32 v24, 16, v47
	v_and_b32_e32 v25, 0xffff0000, v47
	global_store_dwordx4 v[2:3], v[22:25], off
	s_add_i32 s1, 0, 0x18000
	v_add_u32_e32 v184, s1, v172
	v_lshlrev_b32_e32 v22, 16, v48
	v_and_b32_e32 v23, 0xffff0000, v48
	v_lshlrev_b32_e32 v24, 16, v49
	v_and_b32_e32 v25, 0xffff0000, v49
	global_store_dwordx4 v[2:3], v[22:25], off offset:16
	v_or_b32_e32 v2, 32, v66
	v_cmp_gt_u32_e64 s[10:11], v2, v67
	v_or_b32_e32 v2, 33, v66
	v_cmp_gt_u32_e64 s[14:15], v2, v67
	v_or_b32_e32 v2, 2, v66
	v_cmp_gt_u32_e64 s[16:17], v2, v67
	v_or_b32_e32 v2, 34, v66
	v_cmp_gt_u32_e64 s[18:19], v2, v67
	v_or_b32_e32 v2, 3, v66
	v_cmp_gt_u32_e64 s[20:21], v2, v67
	v_or_b32_e32 v2, 35, v66
	v_cmp_gt_u32_e64 s[22:23], v2, v67
	v_or_b32_e32 v2, 8, v66
	v_cmp_gt_u32_e64 s[24:25], v2, v67
	v_or_b32_e32 v2, 40, v66
	v_cmp_gt_u32_e64 s[26:27], v2, v67
	v_or_b32_e32 v2, 9, v66
	v_cmp_gt_u32_e64 s[28:29], v2, v67
	v_or_b32_e32 v2, 41, v66
	v_cmp_gt_u32_e64 s[30:31], v2, v67
	v_or_b32_e32 v2, 10, v66
	v_cmp_gt_u32_e64 s[34:35], v2, v67
	v_or_b32_e32 v2, 42, v66
	v_cmp_gt_u32_e64 s[36:37], v2, v67
	v_or_b32_e32 v2, 11, v66
	v_cmp_gt_u32_e64 s[38:39], v2, v67
	v_or_b32_e32 v2, 43, v66
	v_cmp_gt_u32_e64 s[40:41], v2, v67
	v_or_b32_e32 v2, 16, v66
	v_cmp_gt_u32_e64 s[42:43], v2, v67
	v_or_b32_e32 v2, 48, v66
	v_cmp_gt_u32_e64 s[44:45], v2, v67
	v_or_b32_e32 v2, 17, v66
	v_cmp_gt_u32_e64 s[46:47], v2, v67
	v_or_b32_e32 v2, 49, v66
	v_cmp_gt_u32_e64 s[48:49], v2, v67
	v_or_b32_e32 v2, 18, v66
	v_cmp_gt_u32_e64 s[50:51], v2, v67
	v_or_b32_e32 v2, 50, v66
	v_cmp_gt_u32_e64 s[52:53], v2, v67
	v_or_b32_e32 v2, 19, v66
	v_cmp_gt_u32_e64 s[54:55], v2, v67
	v_or_b32_e32 v2, 51, v66
	v_cmp_gt_u32_e64 s[56:57], v2, v67
	v_or_b32_e32 v2, 24, v66
	v_cmp_gt_u32_e64 s[58:59], v2, v67
	v_or_b32_e32 v2, 56, v66
	v_cmp_gt_u32_e64 s[60:61], v2, v67
	v_or_b32_e32 v2, 25, v66
	v_cmp_gt_u32_e64 s[62:63], v2, v67
	v_or_b32_e32 v2, 57, v66
	v_cmp_gt_u32_e64 s[64:65], v2, v67
	v_or_b32_e32 v2, 26, v66
	v_cmp_gt_u32_e64 s[66:67], v2, v67
	v_or_b32_e32 v2, 58, v66
	v_cmp_gt_u32_e64 s[68:69], v2, v67
	v_or_b32_e32 v2, 27, v66
	v_cmp_gt_u32_e64 s[70:71], v2, v67
	v_or_b32_e32 v2, 59, v66
	v_lshlrev_b32_e32 v22, 16, v50
	v_and_b32_e32 v23, 0xffff0000, v50
	v_lshlrev_b32_e32 v24, 16, v51
	v_and_b32_e32 v25, 0xffff0000, v51
	s_add_i32 s1, 0, 0x1a800
	v_cmp_gt_u32_e64 s[8:9], v66, v67
	v_cmp_gt_u32_e64 s[72:73], v2, v67
	v_mov_b32_e32 v66, v5
	v_mov_b32_e32 v67, v5
	global_store_dwordx4 v[26:27], v[22:25], off
	s_bitcmp1_b32 s3, 7
	v_mov_b32_e32 v62, v5
	v_lshlrev_b32_e32 v22, 16, v52
	v_and_b32_e32 v23, 0xffff0000, v52
	v_lshlrev_b32_e32 v24, 16, v53
	v_and_b32_e32 v25, 0xffff0000, v53
	v_mov_b32_e32 v52, v5
	v_mov_b32_e32 v53, v5
	v_mov_b32_e32 v63, v5
	v_mov_b64_e32 v[82:83], v[66:67]
	v_lshl_add_u32 v186, v175, 3, s1
	s_cselect_b64 s[94:95], -1, 0
	s_mov_b32 s1, 0
	v_mov_b32_e32 v159, v5
	v_mov_b32_e32 v192, 0
	v_mov_b32_e32 v124, 0
	v_mov_b32_e32 v125, 0
	v_mov_b32_e32 v126, 0
	v_mov_b32_e32 v127, 0
	v_mov_b32_e32 v128, 0
	v_mov_b32_e32 v129, 0
	v_mov_b32_e32 v130, 0
	v_mov_b32_e32 v131, 0
	v_mov_b32_e32 v132, 0
	v_mov_b32_e32 v133, 0
	v_mov_b32_e32 v134, 0
	v_mov_b32_e32 v135, 0
	v_mov_b32_e32 v136, 0
	v_mov_b32_e32 v137, 0
	v_mov_b32_e32 v138, 0
	v_mov_b32_e32 v139, 0
	v_mov_b32_e32 v140, 0
	v_mov_b32_e32 v141, 0
	v_mov_b32_e32 v142, 0
	v_mov_b32_e32 v143, 0
	v_mov_b32_e32 v144, 0
	v_mov_b32_e32 v145, 0
	v_mov_b32_e32 v146, 0
	v_mov_b32_e32 v147, 0
	v_mov_b32_e32 v148, 0
	v_mov_b32_e32 v149, 0
	v_mov_b32_e32 v150, 0
	v_mov_b32_e32 v151, 0
	v_mov_b32_e32 v152, 0
	v_mov_b32_e32 v153, 0
	v_mov_b32_e32 v154, 0
	v_mov_b32_e32 v155, 0
	v_cndmask_b32_e64 v2, 0, v187, s[6:7]
	s_mov_b32 s75, 0
	v_mov_b64_e32 v[80:81], v[64:65]
	v_mov_b64_e32 v[78:79], v[62:63]
	v_mov_b64_e32 v[76:77], v[60:61]
	v_mov_b64_e32 v[74:75], v[58:59]
	v_mov_b64_e32 v[72:73], v[56:57]
	v_mov_b64_e32 v[70:71], v[54:55]
	v_mov_b64_e32 v[68:69], v[52:53]
	v_mov_b32_e32 v193, 0
	s_mov_b64 s[4:5], 0
	global_store_dwordx4 v[26:27], v[22:25], off offset:16
	s_waitcnt vmcnt(16) lgkmcnt(0)
	s_barrier
	s_branch .Lfox_top_l0

; __device__ __forceinline__ void pv(f32x16 (&o)[2], const VFrags& v, const u32x4& pw0, const u32x4& pw1, const u32x4& pw2, const u32x4& pw3) {
;     ...
;     o[0] = __builtin_amdgcn_mfma_f32_32x32x16_bf16(__builtin_bit_cast(bf16x8, pw0), ATT_VF(0), o[0], 0, 0, 0);
;     o[1] = __builtin_amdgcn_mfma_f32_32x32x16_bf16(__builtin_bit_cast(bf16x8, pw0), ATT_VF(4), o[1], 0, 0, 0);
;     o[0] = __builtin_amdgcn_mfma_f32_32x32x16_bf16(__builtin_bit_cast(bf16x8, pw1), ATT_VF(1), o[0], 0, 0, 0);
;     o[1] = __builtin_amdgcn_mfma_f32_32x32x16_bf16(__builtin_bit_cast(bf16x8, pw1), ATT_VF(5), o[1], 0, 0, 0);
;     o[0] = __builtin_amdgcn_mfma_f32_32x32x16_bf16(__builtin_bit_cast(bf16x8, pw2), ATT_VF(2), o[0], 0, 0, 0);
;     o[1] = __builtin_amdgcn_mfma_f32_32x32x16_bf16(__builtin_bit_cast(bf16x8, pw2), ATT_VF(6), o[1], 0, 0, 0);
;     o[0] = __builtin_amdgcn_mfma_f32_32x32x16_bf16(__builtin_bit_cast(bf16x8, pw3), ATT_VF(3), o[0], 0, 0, 0);
;     o[1] = __builtin_amdgcn_mfma_f32_32x32x16_bf16(__builtin_bit_cast(bf16x8, pw3), ATT_VF(7), o[1], 0, 0, 0);
;     ...
; }
; __device__ __forceinline__ void fox_pair_pv(FoxState& st, const PairP& pp, lds_cptr vpB) {
;     { VFrags vf; vfrags(vf, vpB + 8192); pv(st.o, vf, pp.w[0], pp.w[1], pp.w[2], pp.w[3]); }
;     { VFrags vf; vfrags(vf, vpB); pv(st.o, vf, pp.w[4], pp.w[5], pp.w[6], pp.w[7]); }
; }
.LBB0_315:
	s_andn2_b64 vcc, exec, s[4:5]
	s_cbranch_vccnz .LBB0_317
	v_lshl_add_u32 v3, s1, 14, v180
	ds_read_b64_tr_b16 v[84:85], v3 offset:57344
	ds_read_b64_tr_b16 v[86:87], v3 offset:57856
	ds_read_b64_tr_b16 v[88:89], v3 offset:61440
	ds_read_b64_tr_b16 v[90:91], v3 offset:61952
	ds_read_b64_tr_b16 v[92:93], v3 offset:58368
	ds_read_b64_tr_b16 v[94:95], v3 offset:58880
	ds_read_b64_tr_b16 v[96:97], v3 offset:62464
	ds_read_b64_tr_b16 v[98:99], v3 offset:62976
	ds_read_b64_tr_b16 v[100:101], v3 offset:59392
	ds_read_b64_tr_b16 v[102:103], v3 offset:59904
	ds_read_b64_tr_b16 v[104:105], v3 offset:63488
	ds_read_b64_tr_b16 v[106:107], v3 offset:64000
	ds_read_b64_tr_b16 v[108:109], v3 offset:60416
	ds_read_b64_tr_b16 v[110:111], v3 offset:60928
	s_waitcnt lgkmcnt(12)
	v_mfma_f32_32x32x16_bf16 v[68:83], v[152:155], v[84:87], v[68:83]
	ds_read_b64_tr_b16 v[112:113], v3 offset:64512
	ds_read_b64_tr_b16 v[114:115], v3 offset:65024
	s_waitcnt lgkmcnt(12)
	v_mfma_f32_32x32x16_bf16 v[52:67], v[152:155], v[88:91], v[52:67]
	ds_read_b64_tr_b16 v[84:85], v3 offset:49152
	ds_read_b64_tr_b16 v[86:87], v3 offset:49664
	s_waitcnt lgkmcnt(12)
	v_mfma_f32_32x32x16_bf16 v[68:83], v[148:151], v[92:95], v[68:83]
	ds_read_b64_tr_b16 v[88:89], v3 offset:53248
	ds_read_b64_tr_b16 v[90:91], v3 offset:53760
	s_waitcnt lgkmcnt(12)
	v_mfma_f32_32x32x16_bf16 v[52:67], v[148:151], v[96:99], v[52:67]
	ds_read_b64_tr_b16 v[92:93], v3 offset:50176
	ds_read_b64_tr_b16 v[94:95], v3 offset:50688
	s_waitcnt lgkmcnt(12)
	v_mfma_f32_32x32x16_bf16 v[68:83], v[144:147], v[100:103], v[68:83]
	ds_read_b64_tr_b16 v[96:97], v3 offset:54272
	ds_read_b64_tr_b16 v[98:99], v3 offset:54784
	s_waitcnt lgkmcnt(12)
	v_mfma_f32_32x32x16_bf16 v[52:67], v[144:147], v[104:107], v[52:67]
	ds_read_b64_tr_b16 v[100:101], v3 offset:51200
	ds_read_b64_tr_b16 v[102:103], v3 offset:51712
	s_waitcnt lgkmcnt(12)
	v_mfma_f32_32x32x16_bf16 v[68:83], v[140:143], v[108:111], v[68:83]
	ds_read_b64_tr_b16 v[104:105], v3 offset:55296
	ds_read_b64_tr_b16 v[106:107], v3 offset:55808
	s_waitcnt lgkmcnt(12)
	v_mfma_f32_32x32x16_bf16 v[52:67], v[140:143], v[112:115], v[52:67]
	ds_read_b64_tr_b16 v[108:109], v3 offset:52224
	ds_read_b64_tr_b16 v[110:111], v3 offset:52736
	s_waitcnt lgkmcnt(12)
	v_mfma_f32_32x32x16_bf16 v[68:83], v[136:139], v[84:87], v[68:83]
	ds_read_b64_tr_b16 v[112:113], v3 offset:56320
	ds_read_b64_tr_b16 v[114:115], v3 offset:56832
	s_waitcnt lgkmcnt(12)
	v_mfma_f32_32x32x16_bf16 v[52:67], v[136:139], v[88:91], v[52:67]
	s_waitcnt lgkmcnt(10)
	v_mfma_f32_32x32x16_bf16 v[68:83], v[132:135], v[92:95], v[68:83]
	s_waitcnt lgkmcnt(8)
	v_mfma_f32_32x32x16_bf16 v[52:67], v[132:135], v[96:99], v[52:67]
	s_waitcnt lgkmcnt(6)
	v_mfma_f32_32x32x16_bf16 v[68:83], v[128:131], v[100:103], v[68:83]
	s_waitcnt lgkmcnt(4)
	v_mfma_f32_32x32x16_bf16 v[52:67], v[128:131], v[104:107], v[52:67]
	s_waitcnt lgkmcnt(2)
	v_mfma_f32_32x32x16_bf16 v[68:83], v[124:127], v[108:111], v[68:83]
	s_waitcnt lgkmcnt(0)
	v_mfma_f32_32x32x16_bf16 v[52:67], v[124:127], v[112:115], v[52:67]

; #define LAS __attribute__((address_space(3)))
; __device__ __forceinline__ bool fox_pair_qs(FoxState& st, PairP& pp, lds_cptr kslotB, const bf16x8 (&qr)[4], const LAS u32x2* augB  , bool careful, int r32, int hi, LAS float* wsf) {
;     bf16x8 kfA[8], kfB[8]; kfrags(kfA, kslotB + 8192, r32, hi); kfrags(kfB, kslotB, r32, hi);
;     const u32x2 t0 = augB[64], t1 = augB[96], t2 = augB[0], t3 = augB[32];
;     const f32x16 zz = {};
;     f32x16 a0, a1, b0, b1;
;     a0 = __builtin_amdgcn_mfma_f32_32x32x16_bf16(__builtin_bit_cast(bf16x8, (u32x4){t0.x, t0.y, 0xBF80BF80u, 0u}), st.mq, zz, 0, 0, 0);
;     a1 = __builtin_amdgcn_mfma_f32_32x32x16_bf16(__builtin_bit_cast(bf16x8, (u32x4){t1.x, t1.y, 0xBF80BF80u, 0u}), st.mq, zz, 0, 0, 0);
;     b0 = __builtin_amdgcn_mfma_f32_32x32x16_bf16(__builtin_bit_cast(bf16x8, (u32x4){t2.x, t2.y, 0xBF80BF80u, 0u}), st.mq, zz, 0, 0, 0);
;     b1 = __builtin_amdgcn_mfma_f32_32x32x16_bf16(__builtin_bit_cast(bf16x8, (u32x4){t3.x, t3.y, 0xBF80BF80u, 0u}), st.mq, zz, 0, 0, 0);
; #pragma unroll
;     for (int d0 = 0; d0 < 4; ++d0) {
;         a0 = __builtin_amdgcn_mfma_f32_32x32x16_bf16(kfA[2 * d0], qr[d0], a0, 0, 0, 0); a1 = __builtin_amdgcn_mfma_f32_32x32x16_bf16(kfA[2 * d0 + 1], qr[d0], a1, 0, 0, 0);
;         b0 = __builtin_amdgcn_mfma_f32_32x32x16_bf16(kfB[2 * d0], qr[d0], b0, 0, 0, 0); b1 = __builtin_amdgcn_mfma_f32_32x32x16_bf16(kfB[2 * d0 + 1], qr[d0], b1, 0, 0, 0);
;     }
.LBB0_330:
	ds_read_b64 v[56:57], v124 offset:512
	ds_read_b64 v[60:61], v124 offset:768
	ds_read_b64 v[52:53], v124
	ds_read_b64 v[70:71], v124 offset:256
	ds_read_b128 v[196:199], v125 offset:8192
	ds_read_b128 v[200:203], v125 offset:8704
	ds_read_b128 v[204:207], v125
	ds_read_b128 v[208:211], v125 offset:512
	ds_read_b128 v[220:223], v125 offset:10240
	ds_read_b128 v[224:227], v125 offset:10752
	ds_read_b128 v[228:231], v125 offset:2048
	ds_read_b128 v[232:235], v125 offset:2560
	v_mov_b64_e32 v[58:59], s[86:87]
	v_mov_b64_e32 v[62:63], s[86:87]
	v_mov_b64_e32 v[54:55], s[86:87]
	v_mov_b64_e32 v[72:73], s[86:87]
	s_xor_b64 s[4:5], s[82:83], -1
	s_and_b64 vcc, exec, s[4:5]
	s_waitcnt lgkmcnt(11)
	v_mfma_f32_32x32x16_bf16 v[84:99], v[56:59], v[160:163], 0
	s_waitcnt lgkmcnt(10)
	v_mfma_f32_32x32x16_bf16 v[100:115], v[60:63], v[160:163], 0
	s_waitcnt lgkmcnt(9)
	v_mfma_f32_32x32x16_bf16 v[52:67], v[52:55], v[160:163], 0
	s_waitcnt lgkmcnt(8)
	v_mfma_f32_32x32x16_bf16 v[68:83], v[70:73], v[160:163], 0
	s_waitcnt lgkmcnt(7)
	v_mfma_f32_32x32x16_bf16 v[84:99], v[196:199], v[6:9], v[84:99]
	ds_read_b128 v[196:199], v125 offset:12288
	s_waitcnt lgkmcnt(7)
	v_mfma_f32_32x32x16_bf16 v[100:115], v[200:203], v[6:9], v[100:115]
	ds_read_b128 v[200:203], v125 offset:12800
	s_waitcnt lgkmcnt(7)
	v_mfma_f32_32x32x16_bf16 v[52:67], v[204:207], v[6:9], v[52:67]
	ds_read_b128 v[204:207], v125 offset:4096
	s_waitcnt lgkmcnt(7)
	v_mfma_f32_32x32x16_bf16 v[68:83], v[208:211], v[6:9], v[68:83]
	ds_read_b128 v[208:211], v125 offset:4608
	s_waitcnt lgkmcnt(7)
	v_mfma_f32_32x32x16_bf16 v[84:99], v[220:223], v[10:13], v[84:99]
	ds_read_b128 v[220:223], v125 offset:14336
	s_waitcnt lgkmcnt(7)
	v_mfma_f32_32x32x16_bf16 v[100:115], v[224:227], v[10:13], v[100:115]
	ds_read_b128 v[224:227], v125 offset:14848
	s_waitcnt lgkmcnt(7)
	v_mfma_f32_32x32x16_bf16 v[52:67], v[228:231], v[10:13], v[52:67]
	ds_read_b128 v[228:231], v125 offset:6144
	s_waitcnt lgkmcnt(7)
	v_mfma_f32_32x32x16_bf16 v[68:83], v[232:235], v[10:13], v[68:83]
	ds_read_b128 v[232:235], v125 offset:6656
	s_waitcnt lgkmcnt(7)
	v_mfma_f32_32x32x16_bf16 v[84:99], v[196:199], v[14:17], v[84:99]
	s_waitcnt lgkmcnt(6)
	v_mfma_f32_32x32x16_bf16 v[100:115], v[200:203], v[14:17], v[100:115]
	s_waitcnt lgkmcnt(5)
	v_mfma_f32_32x32x16_bf16 v[52:67], v[204:207], v[14:17], v[52:67]
	s_waitcnt lgkmcnt(4)
	v_mfma_f32_32x32x16_bf16 v[68:83], v[208:211], v[14:17], v[68:83]
	s_waitcnt lgkmcnt(3)
	v_mfma_f32_32x32x16_bf16 v[84:99], v[220:223], v[116:119], v[84:99]
	s_waitcnt lgkmcnt(2)
	v_mfma_f32_32x32x16_bf16 v[100:115], v[224:227], v[116:119], v[100:115]
	s_waitcnt lgkmcnt(1)
	v_mfma_f32_32x32x16_bf16 v[52:67], v[228:231], v[116:119], v[52:67]
	s_waitcnt lgkmcnt(0)
	v_mfma_f32_32x32x16_bf16 v[68:83], v[232:235], v[116:119], v[68:83]
	s_nop 2
	s_cbranch_vccnz .LBB0_334
; #define LAS __attribute__((address_space(3)))
; __device__ __forceinline__ float swap_max(float m) { auto rr = __builtin_amdgcn_permlane32_swap(__float_as_uint(m), __float_as_uint(m), false, false); return fmaxf(__uint_as_float(rr[0]), __uint_as_float(rr[1])); }
; __device__ __forceinline__ float max3f(float a, float b, float c) { return __builtin_fmaxf(__builtin_fmaxf(a, b), c); }
; #define ATT_LDS_WAIT() asm volatile("s_waitcnt lgkmcnt(0)" ::: "memory")
; __device__ __forceinline__ bool fox_pair_qs(FoxState& st, PairP& pp, lds_cptr kslotB, const bf16x8 (&qr)[4], const LAS u32x2* augB  , bool careful, int r32, int hi, LAS float* wsf) {
;     ...
;     if (careful) {
;         asm volatile("; careful pass: move the reference" ::: "memory");
;         float rm = max3f(a0[0], a1[0], b0[0]), rm2 = max3f(b1[0], a0[1], a1[1]);
;         rm = max3f(rm, b0[1], b1[1]);
; #pragma unroll
;         for (int r = 2; r < 16; ++r) { rm = max3f(rm, a0[r], a1[r]); rm2 = max3f(rm2, b0[r], b1[r]); }
;         rm = swap_max(max3f(rm, rm2, rm2));
;         const float dl = fmaxf(rm, 0.f);
;         st.m += dl; st.mq = make_mq(st.m, hi);
; #pragma unroll
;         for (int r = 0; r < 16; ++r) { a0[r] -= dl; a1[r] -= dl; b0[r] -= dl; b1[r] -= dl; }
;         const float f = __builtin_amdgcn_exp2f(-dl);
;         st.l *= f;
;         if (hi == 0) wsf[r32] = f;
;         ATT_LDS_WAIT();
; #pragma unroll
;         for (int g = 0; g < 4; ++g) { const f32x4 fv = *(const LAS f32x4*)(wsf + 8 * g + 4 * hi);
; #pragma unroll
;             for (int i = 0; i < 4; ++i) { st.o[0][4 * g + i] *= fv[i]; st.o[1][4 * g + i] *= fv[i]; } }
;     }
	s_nop 4
	v_max_f32_e32 v3, v100, v100
	v_max_f32_e32 v4, v84, v84
	v_max_f32_e32 v3, v4, v3
	s_nop 2
	v_max3_f32 v4, v68, v85, v101
	v_max3_f32 v3, v3, v52, v53
	v_max3_f32 v3, v3, v69, v86
	v_max3_f32 v4, v4, v54, v70
	v_max3_f32 v3, v3, v102, v87
	v_max3_f32 v4, v4, v55, v71
	v_max3_f32 v3, v3, v103, v88
	v_max3_f32 v4, v4, v56, v72
	v_max3_f32 v3, v3, v104, v89
	v_max3_f32 v4, v4, v57, v73
	v_max3_f32 v3, v3, v105, v90
	v_max3_f32 v4, v4, v58, v74
	v_max3_f32 v3, v3, v106, v91
	v_max3_f32 v4, v4, v59, v75
	v_max3_f32 v3, v3, v107, v92
	v_max3_f32 v4, v4, v60, v76
	v_max3_f32 v3, v3, v108, v93
	v_max3_f32 v4, v4, v61, v77
	v_max3_f32 v3, v3, v109, v94
	v_max3_f32 v4, v4, v62, v78
	v_max3_f32 v3, v3, v110, v95
	v_max3_f32 v4, v4, v63, v79
	v_max3_f32 v3, v3, v111, v96
	v_max3_f32 v4, v4, v64, v80
	v_max3_f32 v3, v3, v112, v97
	v_max3_f32 v4, v4, v65, v81
	v_max3_f32 v3, v3, v113, v98
	v_max3_f32 v4, v4, v66, v82
	v_max3_f32 v3, v3, v114, v99
	v_max3_f32 v4, v4, v67, v83
	v_max3_f32 v3, v3, v115, v4
	v_mov_b32_e32 v4, v3
	s_nop 1
	v_permlane32_swap_b32_e32 v3, v4
	v_max3_f32 v126, v3, v4, 0
	v_exp_f32_e64 v127, -v126
	s_and_saveexec_b64 vcc, s[6:7]
	ds_write_b32 v182, v127
	s_or_b64 exec, exec, vcc
	v_add_f32_e32 v191, v191, v126
	v_cvt_pk_bf16_f32 v3, v191, 0
	v_lshlrev_b32_e32 v3, 16, v3
	v_sub_f32_e32 v4, v191, v3
	v_cvt_pk_bf16_f32 v128, v4, 0
	v_lshlrev_b32_e32 v128, 16, v128
	v_sub_f32_e32 v4, v4, v128
	s_waitcnt lgkmcnt(0)
	v_add_u32_e32 v138, s78, v172
	v_cvt_pk_bf16_f32 v4, v128, v4
	v_sub_f32_e32 v99, v99, v126
	v_sub_f32_e32 v98, v98, v126
	v_sub_f32_e32 v97, v97, v126
	v_sub_f32_e32 v96, v96, v126
	v_sub_f32_e32 v95, v95, v126
	v_sub_f32_e32 v94, v94, v126
	v_sub_f32_e32 v93, v93, v126
	v_sub_f32_e32 v92, v92, v126
	v_sub_f32_e32 v91, v91, v126
	v_sub_f32_e32 v90, v90, v126
	v_sub_f32_e32 v89, v89, v126
	v_sub_f32_e32 v88, v88, v126
	v_sub_f32_e32 v87, v87, v126
	v_sub_f32_e32 v86, v86, v126
	v_sub_f32_e32 v85, v85, v126
	v_sub_f32_e32 v84, v84, v126
	v_sub_f32_e32 v115, v115, v126
	v_sub_f32_e32 v114, v114, v126
	v_sub_f32_e32 v113, v113, v126
	v_sub_f32_e32 v112, v112, v126
	v_sub_f32_e32 v111, v111, v126
	v_sub_f32_e32 v110, v110, v126
	v_sub_f32_e32 v109, v109, v126
	v_sub_f32_e32 v108, v108, v126
	v_sub_f32_e32 v107, v107, v126
	v_sub_f32_e32 v106, v106, v126
	v_sub_f32_e32 v105, v105, v126
	v_sub_f32_e32 v104, v104, v126
	v_sub_f32_e32 v103, v103, v126
	v_sub_f32_e32 v102, v102, v126
	v_sub_f32_e32 v101, v101, v126
	v_sub_f32_e32 v100, v100, v126
	v_sub_f32_e32 v67, v67, v126
	v_sub_f32_e32 v66, v66, v126
	v_sub_f32_e32 v65, v65, v126
	v_sub_f32_e32 v64, v64, v126
	v_sub_f32_e32 v63, v63, v126
	v_sub_f32_e32 v62, v62, v126
	v_sub_f32_e32 v61, v61, v126
	v_sub_f32_e32 v60, v60, v126
	v_sub_f32_e32 v59, v59, v126
	v_sub_f32_e32 v58, v58, v126
	v_sub_f32_e32 v57, v57, v126
	v_sub_f32_e32 v56, v56, v126
	v_sub_f32_e32 v55, v55, v126
	v_sub_f32_e32 v54, v54, v126
	v_sub_f32_e32 v53, v53, v126
	v_sub_f32_e32 v52, v52, v126
	v_sub_f32_e32 v83, v83, v126
	v_sub_f32_e32 v82, v82, v126
	v_sub_f32_e32 v81, v81, v126
	v_sub_f32_e32 v80, v80, v126
	v_sub_f32_e32 v79, v79, v126
	v_sub_f32_e32 v78, v78, v126
	v_sub_f32_e32 v77, v77, v126
	v_sub_f32_e32 v76, v76, v126
	v_sub_f32_e32 v75, v75, v126
	v_sub_f32_e32 v74, v74, v126
	v_sub_f32_e32 v73, v73, v126
	v_sub_f32_e32 v72, v72, v126
	v_sub_f32_e32 v71, v71, v126
	v_sub_f32_e32 v70, v70, v126
	v_sub_f32_e32 v69, v69, v126
	v_sub_f32_e32 v68, v68, v126
	v_mul_f32_e32 v194, v194, v127
	ds_read_b128 v[126:129], v138
	ds_read_b128 v[130:133], v138 offset:32
	ds_read_b128 v[134:137], v138 offset:64
	ds_read_b128 v[138:141], v138 offset:96
	v_cvt_pk_bf16_f32 v3, 1.0, v3
	v_cndmask_b32_e64 v4, 0, v4, s[6:7]
	v_cndmask_b32_e64 v3, 0, v3, s[6:7]
	v_mov_b64_e32 v[162:163], v[4:5]
	s_waitcnt lgkmcnt(0)
	v_pk_mul_f32 v[32:33], v[32:33], v[138:139]
	v_pk_mul_f32 v[28:29], v[28:29], v[134:135]
	v_pk_mul_f32 v[24:25], v[24:25], v[130:131]
	v_pk_mul_f32 v[34:35], v[34:35], v[140:141]
	v_pk_mul_f32 v[30:31], v[30:31], v[136:137]
	v_pk_mul_f32 v[26:27], v[26:27], v[132:133]
	v_pk_mul_f32 v[22:23], v[22:23], v[128:129]
	v_pk_mul_f32 v[20:21], v[20:21], v[126:127]
	v_pk_mul_f32 v[48:49], v[48:49], v[138:139]
	v_pk_mul_f32 v[44:45], v[44:45], v[134:135]
	v_pk_mul_f32 v[40:41], v[40:41], v[130:131]
	v_pk_mul_f32 v[50:51], v[50:51], v[140:141]
	v_pk_mul_f32 v[46:47], v[46:47], v[136:137]
	v_pk_mul_f32 v[42:43], v[42:43], v[132:133]
	v_pk_mul_f32 v[38:39], v[38:39], v[128:129]
	v_pk_mul_f32 v[36:37], v[36:37], v[126:127]
	v_mov_b64_e32 v[160:161], v[2:3]

; __device__ __forceinline__ void pv(f32x16 (&o)[2], const VFrags& v, const u32x4& pw0, const u32x4& pw1, const u32x4& pw2, const u32x4& pw3) {
;     ...
;     o[0] = __builtin_amdgcn_mfma_f32_32x32x16_bf16(__builtin_bit_cast(bf16x8, pw0), ATT_VF(0), o[0], 0, 0, 0);
;     o[1] = __builtin_amdgcn_mfma_f32_32x32x16_bf16(__builtin_bit_cast(bf16x8, pw0), ATT_VF(4), o[1], 0, 0, 0);
;     o[0] = __builtin_amdgcn_mfma_f32_32x32x16_bf16(__builtin_bit_cast(bf16x8, pw1), ATT_VF(1), o[0], 0, 0, 0);
;     o[1] = __builtin_amdgcn_mfma_f32_32x32x16_bf16(__builtin_bit_cast(bf16x8, pw1), ATT_VF(5), o[1], 0, 0, 0);
;     o[0] = __builtin_amdgcn_mfma_f32_32x32x16_bf16(__builtin_bit_cast(bf16x8, pw2), ATT_VF(2), o[0], 0, 0, 0);
;     o[1] = __builtin_amdgcn_mfma_f32_32x32x16_bf16(__builtin_bit_cast(bf16x8, pw2), ATT_VF(6), o[1], 0, 0, 0);
;     o[0] = __builtin_amdgcn_mfma_f32_32x32x16_bf16(__builtin_bit_cast(bf16x8, pw3), ATT_VF(3), o[0], 0, 0, 0);
;     o[1] = __builtin_amdgcn_mfma_f32_32x32x16_bf16(__builtin_bit_cast(bf16x8, pw3), ATT_VF(7), o[1], 0, 0, 0);
;     ...
; }
; __device__ __forceinline__ bool fox_pair_qs(FoxState& st, PairP& pp, lds_cptr kslotB, const bf16x8 (&qr)[4], const LAS u32x2* augB  , bool careful, int r32, int hi, LAS float* wsf) {
;     ...
;     float sacc = 0.f, sacc2 = 0.f;
; #pragma unroll
;     for (int r = 0; r < 16; ++r) { a0[r] = __builtin_amdgcn_exp2f(a0[r]); a1[r] = __builtin_amdgcn_exp2f(a1[r]); sacc = fadd_s(sacc, a0[r]); sacc2 = fadd_s(sacc2, a1[r]); }
;     pp.w[0] = ATT_PACK4(a0, 0, cvtpk); pp.w[1] = ATT_PACK4(a0, 8, cvtpk); pp.w[2] = ATT_PACK4(a1, 0, cvtpk); pp.w[3] = ATT_PACK4(a1, 8, cvtpk);
; #pragma unroll
;     for (int r = 0; r < 16; ++r) { b0[r] = __builtin_amdgcn_exp2f(b0[r]); b1[r] = __builtin_amdgcn_exp2f(b1[r]); sacc = fadd_s(sacc, b0[r]); sacc2 = fadd_s(sacc2, b1[r]); }
;     pp.w[4] = ATT_PACK4(b0, 0, cvtpk); pp.w[5] = ATT_PACK4(b0, 8, cvtpk); pp.w[6] = ATT_PACK4(b1, 0, cvtpk); pp.w[7] = ATT_PACK4(b1, 8, cvtpk);
;     const float ts = fadd_s(sacc, sacc2);
;     if (!careful && __any(!(ts < FOX_BIG))) return false;
;     st.l = fadd_s(st.l, ts);
;     return true;
; }
; __device__ __forceinline__ void fox_pair_pv(FoxState& st, const PairP& pp, lds_cptr vpB) {
;     { VFrags vf; vfrags(vf, vpB + 8192); pv(st.o, vf, pp.w[0], pp.w[1], pp.w[2], pp.w[3]); }
;     { VFrags vf; vfrags(vf, vpB); pv(st.o, vf, pp.w[4], pp.w[5], pp.w[6], pp.w[7]); }
; }
.LBB0_341:
	v_cvt_pk_bf16_f32 v152, v84, v100
	v_cvt_pk_bf16_f32 v153, v101, v102
	v_cvt_pk_bf16_f32 v154, v103, v104
	v_cvt_pk_bf16_f32 v155, v105, v106
	v_cvt_pk_bf16_f32 v148, v107, v108
	v_cvt_pk_bf16_f32 v149, v109, v110
	v_cvt_pk_bf16_f32 v150, v111, v112
	v_cvt_pk_bf16_f32 v151, v113, v114
	v_cvt_pk_bf16_f32 v144, v3, v4
	v_cvt_pk_bf16_f32 v145, v85, v86
	v_cvt_pk_bf16_f32 v146, v87, v88
	v_cvt_pk_bf16_f32 v147, v89, v90
	v_cvt_pk_bf16_f32 v140, v91, v92
	v_cvt_pk_bf16_f32 v141, v93, v94
	v_cvt_pk_bf16_f32 v142, v95, v96
	v_cvt_pk_bf16_f32 v143, v97, v98
	v_cvt_pk_bf16_f32 v136, v99, v68
	v_cvt_pk_bf16_f32 v137, v69, v70
	v_cvt_pk_bf16_f32 v138, v71, v72
	v_cvt_pk_bf16_f32 v139, v73, v74
	v_cvt_pk_bf16_f32 v132, v75, v76
	v_cvt_pk_bf16_f32 v133, v77, v78
	v_cvt_pk_bf16_f32 v134, v79, v80
	v_cvt_pk_bf16_f32 v135, v81, v82
	v_cvt_pk_bf16_f32 v128, v52, v53
	v_cvt_pk_bf16_f32 v129, v54, v55
	v_cvt_pk_bf16_f32 v130, v56, v57
	v_cvt_pk_bf16_f32 v131, v58, v59
	v_cvt_pk_bf16_f32 v124, v60, v61
	v_cvt_pk_bf16_f32 v125, v62, v63
	v_cvt_pk_bf16_f32 v126, v64, v65
	v_cvt_pk_bf16_f32 v127, v66, v67
	s_andn2_b64 vcc, exec, s[92:93]
	s_mov_b64 s[4:5], -1
	s_cbranch_vccnz .LBB0_344
	ds_read_b64_tr_b16 v[84:85], v190 offset:57344
	ds_read_b64_tr_b16 v[86:87], v190 offset:57856
	ds_read_b64_tr_b16 v[88:89], v190 offset:61440
	ds_read_b64_tr_b16 v[90:91], v190 offset:61952
	ds_read_b64_tr_b16 v[92:93], v190 offset:58368
	ds_read_b64_tr_b16 v[94:95], v190 offset:58880
	ds_read_b64_tr_b16 v[96:97], v190 offset:62464
	ds_read_b64_tr_b16 v[98:99], v190 offset:62976
	ds_read_b64_tr_b16 v[100:101], v190 offset:59392
	ds_read_b64_tr_b16 v[102:103], v190 offset:59904
	ds_read_b64_tr_b16 v[104:105], v190 offset:63488
	ds_read_b64_tr_b16 v[106:107], v190 offset:64000
	ds_read_b64_tr_b16 v[108:109], v190 offset:60416
	ds_read_b64_tr_b16 v[110:111], v190 offset:60928
	s_mov_b64 s[4:5], 0
	s_waitcnt lgkmcnt(12)
	v_mfma_f32_32x32x16_bf16 v[20:35], v[152:155], v[84:87], v[20:35]
	ds_read_b64_tr_b16 v[112:113], v190 offset:64512
	ds_read_b64_tr_b16 v[114:115], v190 offset:65024
	s_waitcnt lgkmcnt(12)
	v_mfma_f32_32x32x16_bf16 v[36:51], v[152:155], v[88:91], v[36:51]
	ds_read_b64_tr_b16 v[84:85], v190 offset:49152
	ds_read_b64_tr_b16 v[86:87], v190 offset:49664
	s_waitcnt lgkmcnt(12)
	v_mfma_f32_32x32x16_bf16 v[20:35], v[148:151], v[92:95], v[20:35]
	ds_read_b64_tr_b16 v[88:89], v190 offset:53248
	ds_read_b64_tr_b16 v[90:91], v190 offset:53760
	s_waitcnt lgkmcnt(12)
	v_mfma_f32_32x32x16_bf16 v[36:51], v[148:151], v[96:99], v[36:51]
	ds_read_b64_tr_b16 v[92:93], v190 offset:50176
	ds_read_b64_tr_b16 v[94:95], v190 offset:50688
	s_waitcnt lgkmcnt(12)
	v_mfma_f32_32x32x16_bf16 v[20:35], v[144:147], v[100:103], v[20:35]
	ds_read_b64_tr_b16 v[96:97], v190 offset:54272
	ds_read_b64_tr_b16 v[98:99], v190 offset:54784
	s_waitcnt lgkmcnt(12)
	v_mfma_f32_32x32x16_bf16 v[36:51], v[144:147], v[104:107], v[36:51]
	ds_read_b64_tr_b16 v[100:101], v190 offset:51200
	ds_read_b64_tr_b16 v[102:103], v190 offset:51712
	s_waitcnt lgkmcnt(12)
	v_mfma_f32_32x32x16_bf16 v[20:35], v[140:143], v[108:111], v[20:35]
	ds_read_b64_tr_b16 v[104:105], v190 offset:55296
	ds_read_b64_tr_b16 v[106:107], v190 offset:55808
	s_waitcnt lgkmcnt(12)
	v_mfma_f32_32x32x16_bf16 v[36:51], v[140:143], v[112:115], v[36:51]
	ds_read_b64_tr_b16 v[108:109], v190 offset:52224
	ds_read_b64_tr_b16 v[110:111], v190 offset:52736
	s_waitcnt lgkmcnt(12)
	v_mfma_f32_32x32x16_bf16 v[20:35], v[136:139], v[84:87], v[20:35]
	ds_read_b64_tr_b16 v[112:113], v190 offset:56320
	ds_read_b64_tr_b16 v[114:115], v190 offset:56832
	s_waitcnt lgkmcnt(12)
	v_mfma_f32_32x32x16_bf16 v[36:51], v[136:139], v[88:91], v[36:51]
	s_waitcnt lgkmcnt(10)
	v_mfma_f32_32x32x16_bf16 v[20:35], v[132:135], v[92:95], v[20:35]
	s_waitcnt lgkmcnt(8)
	v_mfma_f32_32x32x16_bf16 v[36:51], v[132:135], v[96:99], v[36:51]
	s_waitcnt lgkmcnt(6)
	v_mfma_f32_32x32x16_bf16 v[20:35], v[128:131], v[100:103], v[20:35]
	s_waitcnt lgkmcnt(4)
	v_mfma_f32_32x32x16_bf16 v[36:51], v[128:131], v[104:107], v[36:51]
	s_waitcnt lgkmcnt(2)
	v_mfma_f32_32x32x16_bf16 v[20:35], v[124:127], v[108:111], v[20:35]
	s_waitcnt lgkmcnt(0)
	v_mfma_f32_32x32x16_bf16 v[36:51], v[124:127], v[112:115], v[36:51]
	s_branch .LBB0_345

; #define LAS __attribute__((address_space(3)))
; #define ATT_DMA(jt, slot) do { glds16(ksrc + (size_t)(jt) * 64 * D, (unsigned)__builtin_amdgcn_readfirstlane(lds0 + A_K + (slot) * 8192 + wid * 1024)); \
;                                glds16(vsrc + (size_t)(jt) * 64 * D, (unsigned)__builtin_amdgcn_readfirstlane(lds0 + A_V + (slot) * 8192 + wid * 1024)); } while (0)
; __device__ __forceinline__ void conv_load(ConvRegs& c, const Args& a, size_t rowq, int col, int lane) {
; #pragma unroll
;     for (int i = 0; i < 4; ++i) { const size_t grow = rowq + i * 8 + (lane >> 3);
;         c.k[i] = *(const u32x4*)((const bf16*)(a.ws + WS_K) + grow * D + col + (lane & 7) * 8); c.v[i] = *(const u32x4*)((const bf16*)(a.ws + WS_V) + grow * D + col + (lane & 7) * 8); }
; __device__ __forceinline__ void prompt_unit_sb(const Args& a, int l, int b, int h, int qb, LAS unsigned char* lds) {
;     ...
;     f16x8 T00, T01; make_tri(T00, T01, r32, hi);
;     const int q0 = qb * 256, jb = q0 / 64, jd = jb + (wid >> 1);
;     const int col = W + h * HD;
;     const size_t rowb = (size_t)b * T;
;     const bf16* Kh = (const bf16*)(a.ws + WS_K) + rowb * D + col; const bf16* Vh = (const bf16*)(a.ws + WS_V) + rowb * D + col;
;     const unsigned lds0 = (unsigned)(uintptr_t)lds;
;     const bf16* ksrc = Kh + (size_t)lane * D + wid * 8;
;     const bf16* vsrc = Vh + (size_t)(16 * (wid & 3) + (lane >> 2)) * D + (wid >> 2) * 32 + (lane & 3) * 8;
;     ...
;     ATT_DMA(jb + 3); ATT_DMA(jb + 2); ATT_DMA(jb + 1); ATT_DMA(jb);
;     if (jb >= 4) { ATT_DMA(jb - 1); ATT_DMA(jb - 2); ATT_DMA(jb - 3); }
;     bf16x8 qr[4];
;     { const bf16* Qw = (const bf16*)(a.ws + WS_Q) + (rowb + q0 + wid * 32 + r32) * D + col;
; #pragma unroll
;       for (int d0 = 0; d0 < 4; ++d0) qr[d0] = *(const bf16x8*)(Qw + d0 * 16 + hi * 8); }
;     const lds_cptr vp0 = (lds_cptr)lds + B_V + ((lane >> 4) & 1) * 32 + (lane & 3) * 8 + (4 * hi + ((lane & 15) >> 2)) * 64;
;     const int qlim = 32 * (wid & 1) + r32;
;     LAS float* wsf = (LAS float*)(lds + B_WSF) + wid * 64;
;     LAS unsigned* flags = (LAS unsigned*)(lds + B_FLAG);
;     FoxState st; st.m = 0.f; st.l = 0.f; st.mq = (bf16x8){}; st.o[0] = (f32x16){}; st.o[1] = (f32x16){};
;     float R = 0.f; bool done = false;
;     { ConvRegs cv; conv_load(cv, a, rowb + q0 + wid * 32, col, lane); conv_store<1>(cv, a, l, h, rowb + q0 + wid * 32, lane); }
.LBB0_928:
	v_lshrrev_b32_e32 v46, 5, v53
	v_and_b32_e32 v169, 31, v19
	v_lshlrev_b32_e32 v47, 2, v46
	v_cmp_lt_u32_e32 vcc, v47, v169
	v_or_b32_e32 v48, 16, v47
	v_or_b32_e32 v50, 1, v47
	v_cndmask_b32_e64 v3, v179, 0, vcc
	v_cmp_lt_u32_e32 vcc, v48, v169
	v_or_b32_e32 v49, 2, v47
	s_lshl_b32 s3, s7, 8
	v_cndmask_b32_e64 v24, v179, 0, vcc
	v_cmp_lt_u32_e32 vcc, v50, v169
	v_or_b32_e32 v52, 17, v47
	s_ashr_i32 s2, s8, 7
	v_cndmask_b32_e64 v14, v179, 0, vcc
	v_cmp_lt_u32_e32 vcc, v49, v169
	s_ashr_i32 s7, s3, 31
	v_or_b32_e32 v51, 18, v47
	v_cndmask_b32_e64 v15, v179, 0, vcc
	v_cmp_lt_u32_e32 vcc, v52, v169
	s_add_u32 s3, s3, s9
	v_or_b32_e32 v55, 3, v47
	v_cndmask_b32_e64 v25, v179, 0, vcc
	v_cmp_lt_u32_e32 vcc, v51, v169
	s_addc_u32 s7, s7, 0
	s_lshl_b32 s8, s84, 5
	v_cndmask_b32_e64 v26, v179, 0, vcc
	v_or_b32_e32 v54, 8, v47
	v_cmp_lt_u32_e32 vcc, v55, v169
	s_ashr_i32 s9, s8, 31
	v_or_b32_e32 v57, 19, v47
	v_cndmask_b32_e64 v16, v179, 0, vcc
	v_cmp_lt_u32_e32 vcc, v54, v169
	s_add_u32 s82, s3, s8
	v_or_b32_e32 v56, 24, v47
	v_cndmask_b32_e64 v17, v179, 0, vcc
	v_cmp_lt_u32_e32 vcc, v57, v169
	s_addc_u32 s83, s7, s9
	v_or_b32_e32 v58, 10, v47
	v_cndmask_b32_e64 v27, v179, 0, vcc
	v_cmp_lt_u32_e32 vcc, v56, v169
	v_or_b32_e32 v160, s82, v169
	v_mov_b32_e32 v161, s83
	v_readlane_b32 s10, v242, 28
	v_cndmask_b32_e64 v28, v179, 0, vcc
	v_or_b32_e32 v59, 9, v47
	v_cmp_lt_u32_e32 vcc, v58, v169
	v_lshlrev_b64 v[6:7], 11, v[160:161]
	v_readlane_b32 s11, v242, 29
	v_cndmask_b32_e64 v22, v179, 0, vcc
	v_cmp_lt_u32_e32 vcc, v59, v169
	v_or_b32_e32 v60, 26, v47
	v_lshl_add_u64 v[6:7], s[10:11], 0, v[6:7]
	s_lshl_b32 s78, s6, 1
	s_mov_b32 s79, s87
	v_lshrrev_b32_e32 v1, 3, v53
	v_cndmask_b32_e64 v23, v179, 0, vcc
	v_or_b32_e32 v61, 25, v47
	v_lshl_add_u64 v[6:7], v[6:7], 0, s[78:79]
	v_lshlrev_b32_e32 v4, 4, v46
	v_or_b32_e32 v160, s82, v1
	v_readlane_b32 s10, v242, 20
	v_cmp_lt_u32_e32 vcc, v60, v169
	v_lshl_add_u64 v[20:21], v[6:7], 0, v[4:5]
	v_lshlrev_b32_e32 v4, 3, v53
	v_lshlrev_b64 v[162:163], 11, v[160:161]
	v_readlane_b32 s11, v242, 21
	v_cndmask_b32_e64 v29, v179, 0, vcc
	v_cmp_lt_u32_e32 vcc, v61, v169
	v_or_b32_e32 v62, 11, v47
	v_readlane_b32 s12, v242, 22
	v_and_b32_e32 v168, 56, v4
	v_lshl_add_u64 v[6:7], s[10:11], 0, v[162:163]
	v_cndmask_b32_e64 v30, v179, 0, vcc
	v_readlane_b32 s13, v242, 23
	v_cmp_lt_u32_e32 vcc, v62, v169
	v_lshl_add_u64 v[6:7], v[6:7], 0, s[78:79]
	v_lshlrev_b32_e32 v4, 1, v168
	v_lshl_add_u64 v[10:11], s[12:13], 0, v[162:163]
	v_cndmask_b32_e64 v31, v179, 0, vcc
	v_lshl_add_u64 v[6:7], v[6:7], 0, v[4:5]
	v_lshl_add_u64 v[10:11], v[10:11], 0, s[78:79]
	v_pack_b32_f16 v118, v17, v23
	v_pack_b32_f16 v119, v22, v31
	v_or_b32_e32 v63, 27, v47
	v_or_b32_e32 v22, 0x4000, v162
	v_mov_b32_e32 v23, v163
	global_load_dwordx4 v[6:9], v[6:7], off offset:1024
	v_lshl_add_u64 v[10:11], v[10:11], 0, v[4:5]
	v_pack_b32_f16 v117, v15, v16
	v_pack_b32_f16 v116, v3, v14
	v_lshl_add_u64 v[14:15], s[10:11], 0, v[22:23]
	v_cmp_lt_u32_e32 vcc, v63, v169
	global_load_dwordx4 v[10:13], v[10:11], off offset:1024
	v_lshl_add_u64 v[14:15], v[14:15], 0, s[78:79]
	v_cndmask_b32_e64 v3, v179, 0, vcc
	v_lshl_add_u64 v[14:15], v[14:15], 0, v[4:5]
	v_pack_b32_f16 v123, v29, v3
	v_lshlrev_b32_e32 v3, 1, v19
	global_load_dwordx4 v[14:17], v[14:15], off offset:1024
	v_pack_b32_f16 v120, v24, v25
	v_and_b32_e32 v3, 32, v3
	s_add_i32 s3, 0, 0x10000
	v_lshlrev_b32_e32 v24, 4, v19
	global_load_dwordx4 v[124:127], v[20:21], off offset:1024
	global_load_dwordx4 v[128:131], v[20:21], off offset:1056
	global_load_dwordx4 v[132:135], v[20:21], off offset:1088
	global_load_dwordx4 v[136:139], v[20:21], off offset:1120
	v_lshl_add_u64 v[20:21], s[12:13], 0, v[22:23]
	v_add3_u32 v2, s3, v3, v2
	v_lshlrev_b32_e32 v3, 8, v46
	v_and_b32_e32 v24, 0xc0, v24
	v_lshl_add_u64 v[20:21], v[20:21], 0, s[78:79]
	v_add3_u32 v170, v2, v3, v24
	v_or_b32_e32 v2, 0x8000, v162
	v_mov_b32_e32 v3, v163
	v_lshl_add_u64 v[20:21], v[20:21], 0, v[4:5]
	v_lshl_add_u64 v[24:25], s[10:11], 0, v[2:3]
	global_load_dwordx4 v[20:23], v[20:21], off offset:1024
	v_lshl_add_u64 v[24:25], v[24:25], 0, s[78:79]
	v_lshl_add_u64 v[24:25], v[24:25], 0, v[4:5]
	v_lshl_add_u64 v[2:3], s[12:13], 0, v[2:3]
	v_pack_b32_f16 v121, v26, v27
	global_load_dwordx4 v[24:27], v[24:25], off offset:1024
	v_lshl_add_u64 v[2:3], v[2:3], 0, s[78:79]
	v_lshl_add_u64 v[2:3], v[2:3], 0, v[4:5]
	v_pack_b32_f16 v122, v28, v30
	global_load_dwordx4 v[28:31], v[2:3], off offset:1024
	v_or_b32_e32 v2, 0xc000, v162
	v_mov_b32_e32 v3, v163
	v_lshl_add_u64 v[32:33], s[10:11], 0, v[2:3]
	v_lshl_add_u64 v[32:33], v[32:33], 0, s[78:79]
	v_lshl_add_u64 v[2:3], s[12:13], 0, v[2:3]
	v_lshl_add_u64 v[32:33], v[32:33], 0, v[4:5]
	v_lshl_add_u64 v[2:3], v[2:3], 0, s[78:79]
	v_lshl_add_u64 v[2:3], v[2:3], 0, v[4:5]
	global_load_dwordx4 v[32:35], v[32:33], off offset:1024
	s_nop 0
	global_load_dwordx4 v[36:39], v[2:3], off offset:1024
	s_add_u32 s3, s82, 0x10000
	s_addc_u32 s7, s83, 0
	v_and_or_b32 v64, s8, 32, v169
	v_or_b32_e32 v2, s3, v1
	v_mov_b32_e32 v3, s7
	v_readlane_b32 s8, v242, 16
	v_lshlrev_b64 v[2:3], 11, v[2:3]
	v_readlane_b32 s9, v242, 17
	s_lshl_b32 s92, s6, 2
	v_readlane_b32 s6, v242, 24
	v_lshl_add_u64 v[40:41], s[8:9], 0, v[2:3]
	s_mov_b32 s93, s87
	v_readlane_b32 s7, v242, 25
	v_lshl_add_u64 v[40:41], v[40:41], 0, s[92:93]
	v_lshlrev_b32_e32 v4, 2, v168
	v_lshl_add_u64 v[2:3], s[6:7], 0, v[2:3]
	v_lshl_add_u64 v[44:45], v[40:41], 0, v[4:5]
	v_lshl_add_u64 v[2:3], v[2:3], 0, s[92:93]
	v_lshl_add_u64 v[2:3], v[2:3], 0, v[4:5]
	s_movk_i32 s3, 0x4000
	s_mov_b64 s[6:7], 0x4000
	v_lshlrev_b32_e32 v171, 10, v46
	v_cmp_lt_u32_e64 s[10:11], v50, v64
	v_cmp_lt_u32_e64 s[14:15], v49, v64
	v_cmp_lt_u32_e64 s[18:19], v55, v64
	v_cmp_lt_u32_e64 s[22:23], v54, v64
	v_cmp_lt_u32_e64 s[40:41], v48, v64
	v_cmp_lt_u32_e64 s[48:49], v51, v64
	v_or_b32_e32 v54, 58, v47
	v_or_b32_e32 v55, 59, v47
	v_mov_b32_e32 v4, v5
	s_mov_b32 s79, 0
	v_cmp_lt_u32_e64 s[26:27], v59, v64
	s_waitcnt vmcnt(0)
; #define LAS __attribute__((address_space(3)))
; __device__ __forceinline__ float bflo(unsigned w) { return __uint_as_float(w << 16); }
; __device__ __forceinline__ float bfhi(unsigned w) { return __uint_as_float(w & 0xffff0000u); }
; #define ATT_WAIT_BAR_N(N) asm volatile("s_waitcnt vmcnt(" #N ") lgkmcnt(0)\n\ts_barrier" ::: "memory")
; template <int TYPE>
; __device__ __forceinline__ void conv_store(const ConvRegs& c, const Args& a, int l, int h, size_t rowq, int lane) {
; #pragma unroll
;     for (int i = 0; i < 4; ++i) { const size_t grow = rowq + i * 8 + (lane >> 3);
;         float* ko = a.out + (TYPE == 0 ? O_FKP : O_SKP) + ((size_t)l * MP + grow) * W + h * HD + (lane & 7) * 8;
;         float* vo = a.out + (TYPE == 0 ? O_FVP : O_SVP) + ((size_t)l * MP + grow) * W + h * HD + (lane & 7) * 8;
;         const u32x4 kw = c.k[i], vw = c.v[i];
;         __builtin_nontemporal_store((f32x4){bflo(kw.x), bfhi(kw.x), bflo(kw.y), bfhi(kw.y)}, (f32x4*)ko); __builtin_nontemporal_store((f32x4){bflo(kw.z), bfhi(kw.z), bflo(kw.w), bfhi(kw.w)}, (f32x4*)(ko + 4));
;         __builtin_nontemporal_store((f32x4){bflo(vw.x), bfhi(vw.x), bflo(vw.y), bfhi(vw.y)}, (f32x4*)vo); __builtin_nontemporal_store((f32x4){bflo(vw.z), bfhi(vw.z), bflo(vw.w), bfhi(vw.w)}, (f32x4*)(vo + 4)); }
; }
; __device__ __forceinline__ void prompt_unit_sb(const Args& a, int l, int b, int h, int qb, LAS unsigned char* lds) {
;     ...
;     const lds_cptr vp0 = (lds_cptr)lds + B_V + ((lane >> 4) & 1) * 32 + (lane & 3) * 8 + (4 * hi + ((lane & 15) >> 2)) * 64;
;     const int qlim = 32 * (wid & 1) + r32;
;     LAS float* wsf = (LAS float*)(lds + B_WSF) + wid * 64;
;     LAS unsigned* flags = (LAS unsigned*)(lds + B_FLAG);
;     FoxState st; st.m = 0.f; st.l = 0.f; st.mq = (bf16x8){}; st.o[0] = (f32x16){}; st.o[1] = (f32x16){};
;     float R = 0.f; bool done = false;
;     { ConvRegs cv; conv_load(cv, a, rowb + q0 + wid * 32, col, lane); conv_store<1>(cv, a, l, h, rowb + q0 + wid * 32, lane); }
;     for (int it = 0; ; ++it) {
;         const int need = jb - it;
;         if (need >= 3) ATT_WAIT_BAR_N(6); else if (need == 2) ATT_WAIT_BAR_N(4); else if (need == 1) ATT_WAIT_BAR_N(2); else ATT_WAIT_BAR_N(0);
	v_lshlrev_b32_e32 v40, 16, v6
	v_and_b32_e32 v41, 0xffff0000, v6
	v_lshlrev_b32_e32 v42, 16, v7
	v_and_b32_e32 v43, 0xffff0000, v7
	v_lshlrev_b32_e32 v6, 16, v8
	v_and_b32_e32 v7, 0xffff0000, v8
	v_lshlrev_b32_e32 v8, 16, v9
	v_and_b32_e32 v9, 0xffff0000, v9
	global_store_dwordx4 v[44:45], v[6:9], off offset:16
	global_store_dwordx4 v[44:45], v[40:43], off
	v_cmp_lt_u32_e64 s[30:31], v58, v64
	v_lshlrev_b32_e32 v6, 16, v10
	v_and_b32_e32 v7, 0xffff0000, v10
	v_lshlrev_b32_e32 v8, 16, v11
	v_and_b32_e32 v9, 0xffff0000, v11
	global_store_dwordx4 v[2:3], v[6:9], off
	v_lshl_add_u64 v[10:11], v[44:45], 0, s[6:7]
	v_cmp_lt_u32_e64 s[36:37], v62, v64
	v_lshlrev_b32_e32 v6, 16, v12
	v_and_b32_e32 v7, 0xffff0000, v12
	v_lshlrev_b32_e32 v8, 16, v13
	v_and_b32_e32 v9, 0xffff0000, v13
	global_store_dwordx4 v[2:3], v[6:9], off offset:16
	v_lshl_add_u64 v[12:13], v[2:3], 0, s[6:7]
	s_mov_b64 s[6:7], 0x8000
	v_lshlrev_b32_e32 v6, 16, v14
	v_and_b32_e32 v7, 0xffff0000, v14
	v_add_co_u32_e32 v14, vcc, s3, v44
	v_lshlrev_b32_e32 v8, 16, v15
	v_and_b32_e32 v9, 0xffff0000, v15
	v_addc_co_u32_e32 v15, vcc, 0, v45, vcc
	global_store_dwordx4 v[14:15], v[6:9], off
	v_cmp_lt_u32_e64 s[44:45], v52, v64
	v_cmp_lt_u32_e64 s[52:53], v57, v64
	v_lshlrev_b32_e32 v6, 16, v16
	v_and_b32_e32 v7, 0xffff0000, v16
	v_lshlrev_b32_e32 v8, 16, v17
	v_and_b32_e32 v9, 0xffff0000, v17
	global_store_dwordx4 v[10:11], v[6:9], off offset:16
	v_add_co_u32_e32 v10, vcc, s3, v2
	s_nop 0
	v_lshlrev_b32_e32 v6, 16, v20
	v_and_b32_e32 v7, 0xffff0000, v20
	v_lshlrev_b32_e32 v8, 16, v21
	v_and_b32_e32 v9, 0xffff0000, v21
	v_addc_co_u32_e32 v11, vcc, 0, v3, vcc
	s_mov_b32 s3, 0x8000
	global_store_dwordx4 v[10:11], v[6:9], off
	v_add_co_u32_e32 v14, vcc, s3, v44
	s_nop 0
	v_lshlrev_b32_e32 v6, 16, v22
	v_and_b32_e32 v7, 0xffff0000, v22
	v_lshlrev_b32_e32 v8, 16, v23
	v_and_b32_e32 v9, 0xffff0000, v23
	global_store_dwordx4 v[12:13], v[6:9], off offset:16
	v_addc_co_u32_e32 v15, vcc, 0, v45, vcc
	s_nop 0
	v_lshlrev_b32_e32 v6, 16, v24
	v_and_b32_e32 v7, 0xffff0000, v24
	v_lshlrev_b32_e32 v8, 16, v25
	v_and_b32_e32 v9, 0xffff0000, v25
	v_lshl_add_u64 v[10:11], v[44:45], 0, s[6:7]
	global_store_dwordx4 v[14:15], v[6:9], off
	v_lshl_add_u64 v[12:13], v[2:3], 0, s[6:7]
	s_mov_b64 s[6:7], 0xc000
	v_lshlrev_b32_e32 v6, 16, v26
	v_and_b32_e32 v7, 0xffff0000, v26
	v_lshlrev_b32_e32 v8, 16, v27
	v_and_b32_e32 v9, 0xffff0000, v27
	global_store_dwordx4 v[10:11], v[6:9], off offset:16
	v_add_co_u32_e32 v10, vcc, s3, v2
	s_nop 0
	v_lshlrev_b32_e32 v6, 16, v28
	v_and_b32_e32 v7, 0xffff0000, v28
	v_lshlrev_b32_e32 v8, 16, v29
	v_and_b32_e32 v9, 0xffff0000, v29
	v_addc_co_u32_e32 v11, vcc, 0, v3, vcc
	s_mov_b32 s3, 0xc000
	global_store_dwordx4 v[10:11], v[6:9], off
	v_add_co_u32_e32 v14, vcc, s3, v44
	s_nop 0
	v_lshlrev_b32_e32 v6, 16, v30
	v_and_b32_e32 v7, 0xffff0000, v30
	v_lshlrev_b32_e32 v8, 16, v31
	v_and_b32_e32 v9, 0xffff0000, v31
	global_store_dwordx4 v[12:13], v[6:9], off offset:16
	v_addc_co_u32_e32 v15, vcc, 0, v45, vcc
	s_nop 0
	v_lshlrev_b32_e32 v6, 16, v32
	v_and_b32_e32 v7, 0xffff0000, v32
	v_lshlrev_b32_e32 v8, 16, v33
	v_and_b32_e32 v9, 0xffff0000, v33
	v_lshl_add_u64 v[10:11], v[44:45], 0, s[6:7]
	v_lshl_add_u64 v[12:13], v[2:3], 0, s[6:7]
	global_store_dwordx4 v[14:15], v[6:9], off
	v_add_co_u32_e32 v2, vcc, s3, v2
	s_nop 0
	v_lshlrev_b32_e32 v6, 16, v34
	v_and_b32_e32 v7, 0xffff0000, v34
	v_lshlrev_b32_e32 v8, 16, v35
	v_and_b32_e32 v9, 0xffff0000, v35
	global_store_dwordx4 v[10:11], v[6:9], off offset:16
	v_addc_co_u32_e32 v3, vcc, 0, v3, vcc
	s_nop 0
	v_lshlrev_b32_e32 v6, 16, v36
	v_and_b32_e32 v7, 0xffff0000, v36
	v_lshlrev_b32_e32 v8, 16, v37
	v_and_b32_e32 v9, 0xffff0000, v37
	global_store_dwordx4 v[2:3], v[6:9], off
	v_lshlrev_b32_e32 v2, 4, v169
	v_add3_u32 v172, 0, v171, v2
	v_or_b32_e32 v2, 32, v47
	v_cmp_lt_u32_e64 s[8:9], v2, v64
	v_or_b32_e32 v2, 33, v47
	v_cmp_lt_u32_e64 s[12:13], v2, v64
	v_or_b32_e32 v2, 34, v47
	v_cmp_lt_u32_e64 s[16:17], v2, v64
	v_or_b32_e32 v2, 35, v47
	v_cmp_lt_u32_e64 s[20:21], v2, v64
	v_or_b32_e32 v2, 40, v47
	v_cmp_lt_u32_e64 s[24:25], v2, v64
	v_or_b32_e32 v2, 41, v47
	v_cmp_lt_u32_e64 s[28:29], v2, v64
	v_or_b32_e32 v2, 42, v47
	v_cmp_lt_u32_e64 s[34:35], v2, v64
	v_or_b32_e32 v2, 43, v47
	v_cmp_lt_u32_e64 s[38:39], v2, v64
	v_or_b32_e32 v2, 48, v47
	v_cmp_lt_u32_e64 s[42:43], v2, v64
	v_or_b32_e32 v2, 49, v47
	v_cmp_lt_u32_e64 s[46:47], v2, v64
	v_or_b32_e32 v2, 50, v47
	v_cmp_lt_u32_e64 s[50:51], v2, v64
	v_or_b32_e32 v2, 51, v47
	v_cmp_lt_u32_e64 s[54:55], v2, v64
	v_or_b32_e32 v2, 56, v47
	v_lshlrev_b32_e32 v6, 16, v38
	v_and_b32_e32 v7, 0xffff0000, v38
	v_lshlrev_b32_e32 v8, 16, v39
	v_and_b32_e32 v9, 0xffff0000, v39
	s_lshl_b32 s3, s84, 2
	v_cmp_lt_u32_e64 s[58:59], v2, v64
	v_or_b32_e32 v2, 57, v47
	v_mov_b32_e32 v16, v5
	v_mov_b32_e32 v17, v5
	v_and_or_b32 v20, v181, 64, v169
	global_store_dwordx4 v[12:13], v[6:9], off offset:16
	s_add_i32 s93, s3, 0
	v_cmp_lt_u32_e64 s[6:7], v47, v64
	v_cmp_lt_u32_e64 s[62:63], v2, v64
	s_lshl_b32 s3, s1, 15
	s_lshl_b32 s1, s1, 2
	v_mov_b32_e32 v2, v5
	v_mov_b32_e32 v3, v5
	v_mov_b32_e32 v6, v5
	v_mov_b32_e32 v7, v5
	v_mov_b32_e32 v8, v5
	v_mov_b32_e32 v9, v5
	v_mov_b32_e32 v10, v5
	v_mov_b32_e32 v11, v5
	v_mov_b32_e32 v12, v5
	v_mov_b32_e32 v13, v5
	v_mov_b32_e32 v14, v5
	v_mov_b32_e32 v15, v5
	v_lshlrev_b32_e32 v173, 2, v20
	v_mov_b64_e32 v[34:35], v[16:17]
	v_mov_b64_e32 v[50:51], v[16:17]
	s_add_i32 s93, s93, 0x20c00
	v_cmp_lt_u32_e64 s[56:57], v56, v64
	v_cmp_lt_u32_e64 s[60:61], v61, v64
	v_cmp_lt_u32_e64 s[64:65], v60, v64
	s_lshl_b32 s95, s2, 13
	s_sub_i32 s96, 0x30000, s3
	s_sub_i32 s97, s2, s1
	s_sub_i32 s1, 0, s1
	v_mov_b32_e32 v52, 0
	s_mov_b32 s33, 28
	v_mov_b64_e32 v[32:33], v[14:15]
	v_mov_b64_e32 v[30:31], v[12:13]
	v_mov_b64_e32 v[28:29], v[10:11]
	v_mov_b64_e32 v[26:27], v[8:9]
	v_mov_b64_e32 v[24:25], v[6:7]
	v_mov_b64_e32 v[22:23], v[4:5]
	v_mov_b64_e32 v[20:21], v[2:3]
	v_mov_b64_e32 v[48:49], v[14:15]
	v_mov_b64_e32 v[46:47], v[12:13]
	v_mov_b64_e32 v[44:45], v[10:11]
	v_mov_b64_e32 v[42:43], v[8:9]
	v_mov_b64_e32 v[40:41], v[6:7]
	v_mov_b64_e32 v[38:39], v[4:5]
	v_mov_b64_e32 v[36:37], v[2:3]
	v_cmp_lt_u32_e64 s[66:67], v54, v64
	v_cmp_lt_u32_e64 s[68:69], v63, v64
	v_cmp_lt_u32_e64 s[70:71], v55, v64
	v_cmp_eq_u32_e64 s[72:73], 0, v53
	s_mov_b64 s[74:75], 0
	s_add_i32 s89, s1, s33
	s_waitcnt lgkmcnt(0)
	s_barrier
	s_branch .LBB0_942

; #define LAS __attribute__((address_space(3)))
; __device__ __forceinline__ unsigned cvtpk(float lo, float hi) { f32x2 v = {lo, hi}; bf16x2_t b = __builtin_convertvector(v, bf16x2_t); return __builtin_bit_cast(unsigned, b); }
; __device__ __forceinline__ void prompt_unit_fox(const Args& a, int l, int b, int h, int qb, LAS unsigned char* lds) {
;     int tid_ = threadIdx.x; asm volatile("" : "+v"(tid_));
;     const int tid = tid_, lane = tid & 63, r32 = lane & 31, hi = lane >> 5, wid = __builtin_amdgcn_readfirstlane(tid >> 6);
;     const int q0 = qb * 256, NP = (q0 + 256) / 128, jd = q0 / 64 + (wid >> 1), jpd = jd >> 1;
;     const bool lateB = wid >= 4;
;     const int col = h * HD;
;     const size_t rowb = (size_t)b * T;
;     const bf16* Kh = (const bf16*)(a.ws + WS_K) + rowb * D + col; const bf16* Vh = (const bf16*)(a.ws + WS_V) + rowb * D + col;
;     const unsigned lds0 = (unsigned)(uintptr_t)lds;
;     const bf16* ksrc = Kh + (size_t)lane * D + wid * 8;
;     const bf16* vsrc = Vh + (size_t)(16 * (wid & 3) + (lane >> 2)) * D + (wid >> 2) * 32 + (lane & 3) * 8;
;     ...
;     ATT_DMA2(NP - 1, 0);
;     { const int idx = tid * 4; if (idx < q0 + 256) { const f32x4 c = *(const f32x4*)((const float*)(a.ws + WS_CKP) + (size_t)(b * 8 + h) * T + idx); *(LAS f32x4*)(lds + F_CK + idx * 4) = c;
; #pragma unroll
;         for (int e = 0; e < 4; ++e) { const float h1 = bf_hi_part(c[e]), r1 = c[e] - h1, h2 = bf_hi_part(r1), r2 = r1 - h2; ((LAS u32x2*)(lds + F_AUG))[idx + e] = (u32x2){cvtpk(h1, h2), cvtpk(r2, -1.0f)}; } } }
;     bf16x8 qr[4];
;     { const bf16* Qw = (const bf16*)(a.ws + WS_Q) + (rowb + q0 + wid * 32 + r32) * D + col;
; #pragma unroll
;       for (int d0 = 0; d0 < 4; ++d0) qr[d0] = *(const bf16x8*)(Qw + d0 * 16 + hi * 8); }
;     const lds_cptr vp0 = (lds_cptr)lds + F_V + ((lane >> 4) & 1) * 32 + (lane & 3) * 8 + (4 * hi + ((lane & 15) >> 2)) * 64;
;     const int ql = 32 * (wid & 1) + r32, qlim = ql + 1;
;     LAS float* wsf = (LAS float*)(lds + F_WSF) + wid * 64;
;     FoxState st; st.m = 0.f; st.l = 0.f; st.mq = (bf16x8){}; st.o[0] = (f32x16){}; st.o[1] = (f32x16){};
;     PairP pp; bool pending = false;
; #pragma unroll
;     for (int i = 0; i < 8; ++i) pp.w[i] = (u32x4){0u, 0u, 0u, 0u};
;     { ConvRegs cv; conv_load(cv, a, rowb + q0 + wid * 32, col, lane); conv_store<0>(cv, a, l, h, rowb + q0 + wid * 32, lane); }
.LBB0_963:
	v_writelane_b32 v242, s16, 32
	s_or_b64 exec, exec, s[2:3]
	s_lshl_b32 s0, s0, 2
	s_ashr_i32 s2, s6, 7
	s_add_i32 s2, s2, s0
	s_ashr_i32 s0, s2, 1
	s_cmp_lt_i32 s1, 4
	s_cselect_b64 s[90:91], -1, 0
	s_lshl_b32 s2, s8, 11
	s_lshl_b32 s3, s1, 5
	s_or_b32 s2, s9, s2
	s_ashr_i32 s8, s3, 31
	s_add_u32 s79, s3, s2
	v_and_b32_e32 v180, 31, v19
	s_addc_u32 s10, s8, 0
	v_or_b32_e32 v168, s79, v180
	v_mov_b32_e32 v169, s10
	v_readlane_b32 s8, v242, 28
	v_lshlrev_b64 v[2:3], 11, v[168:169]
	v_readlane_b32 s9, v242, 29
	v_lshrrev_b32_e32 v21, 5, v20
	s_lshl_b32 s74, s7, 1
	v_lshl_add_u64 v[2:3], s[8:9], 0, v[2:3]
	s_mov_b32 s75, s87
	v_lshl_add_u64 v[2:3], v[2:3], 0, s[74:75]
	v_lshlrev_b32_e32 v174, 4, v21
	v_mov_b32_e32 v175, v5
	v_lshl_add_u64 v[2:3], v[2:3], 0, v[174:175]
	global_load_dwordx4 v[6:9], v[2:3], off
	global_load_dwordx4 v[10:13], v[2:3], off offset:32
	global_load_dwordx4 v[14:17], v[2:3], off offset:64
	global_load_dwordx4 v[116:119], v[2:3], off offset:96
	v_lshlrev_b32_e32 v2, 1, v19
	v_and_b32_e32 v2, 32, v2
	v_add_u32_e32 v3, 0, v2
	v_lshlrev_b32_e32 v2, 2, v21
	v_lshrrev_b32_e32 v4, 2, v19
	v_and_or_b32 v4, v4, 3, v2
	v_lshlrev_b32_e32 v4, 6, v4
	s_and_b32 s2, s6, 0x3fffffc0
	v_add3_u32 v175, v3, v1, v4
	s_lshl_b32 s2, s2, 2
	v_lshrrev_b32_e32 v1, 3, v20
	v_and_or_b32 v3, s3, 32, v180
	s_add_i32 s89, s2, 0
	v_or_b32_e32 v168, s79, v1
	v_readlane_b32 s2, v242, 20
	v_lshlrev_b32_e32 v4, 3, v20
	v_lshlrev_b64 v[176:177], 11, v[168:169]
	v_readlane_b32 s3, v242, 21
	v_readlane_b32 s8, v242, 22
	v_and_b32_e32 v178, 56, v4
	v_lshl_add_u64 v[22:23], s[2:3], 0, v[176:177]
	v_readlane_b32 s9, v242, 23
	v_lshl_add_u64 v[22:23], v[22:23], 0, s[74:75]
	v_lshlrev_b32_e32 v4, 1, v178
	v_lshl_add_u64 v[26:27], s[8:9], 0, v[176:177]
	v_lshl_add_u64 v[22:23], v[22:23], 0, v[4:5]
	v_lshl_add_u64 v[26:27], v[26:27], 0, s[74:75]
	v_or_b32_e32 v34, 0x4000, v176
	v_mov_b32_e32 v35, v177
	global_load_dwordx4 v[22:25], v[22:23], off
	v_lshl_add_u64 v[26:27], v[26:27], 0, v[4:5]
	v_lshl_add_u64 v[30:31], s[2:3], 0, v[34:35]
	global_load_dwordx4 v[26:29], v[26:27], off
	v_lshl_add_u64 v[30:31], v[30:31], 0, s[74:75]
	v_lshl_add_u64 v[30:31], v[30:31], 0, v[4:5]
	global_load_dwordx4 v[30:33], v[30:31], off
	v_lshl_add_u64 v[34:35], s[8:9], 0, v[34:35]
	v_lshl_add_u64 v[34:35], v[34:35], 0, s[74:75]
	v_lshl_add_u64 v[34:35], v[34:35], 0, v[4:5]
	global_load_dwordx4 v[34:37], v[34:35], off
	v_or_b32_e32 v42, 0x8000, v176
	v_mov_b32_e32 v43, v177
	v_lshl_add_u64 v[38:39], s[2:3], 0, v[42:43]
	v_lshl_add_u64 v[38:39], v[38:39], 0, s[74:75]
	v_lshl_add_u64 v[38:39], v[38:39], 0, v[4:5]
	global_load_dwordx4 v[38:41], v[38:39], off
	v_lshl_add_u64 v[42:43], s[8:9], 0, v[42:43]
	v_lshl_add_u64 v[42:43], v[42:43], 0, s[74:75]
	v_lshl_add_u64 v[42:43], v[42:43], 0, v[4:5]
	global_load_dwordx4 v[42:45], v[42:43], off
	v_or_b32_e32 v50, 0xc000, v176
	v_mov_b32_e32 v51, v177
	v_lshl_add_u64 v[46:47], s[2:3], 0, v[50:51]
	v_lshl_add_u64 v[46:47], v[46:47], 0, s[74:75]
	v_lshl_add_u64 v[46:47], v[46:47], 0, v[4:5]
	global_load_dwordx4 v[46:49], v[46:47], off
	v_lshl_add_u64 v[50:51], s[8:9], 0, v[50:51]
	v_lshl_add_u64 v[50:51], v[50:51], 0, s[74:75]
	v_lshl_add_u64 v[50:51], v[50:51], 0, v[4:5]
	global_load_dwordx4 v[50:53], v[50:51], off
	s_add_i32 s89, s89, 0x1a000
	s_add_u32 s2, s79, 0x10000
	v_writelane_b32 v242, s10, 34
	s_addc_u32 s3, s10, 0
	v_or_b32_e32 v54, s2, v1
	v_mov_b32_e32 v55, s3
	v_readlane_b32 s2, v242, 26
	v_lshlrev_b64 v[54:55], 11, v[54:55]
	v_readlane_b32 s3, v242, 27
	s_lshl_b32 s92, s7, 2
	s_mov_b32 s93, s87
	v_lshl_add_u64 v[56:57], s[2:3], 0, v[54:55]
	v_readlane_b32 s2, v242, 43
	v_readlane_b32 s3, v242, 44
	v_lshl_add_u64 v[56:57], v[56:57], 0, s[92:93]
	v_lshlrev_b32_e32 v4, 2, v178
	v_lshl_add_u64 v[54:55], s[2:3], 0, v[54:55]
	v_lshl_add_u64 v[54:55], v[54:55], 0, s[92:93]
	v_lshl_add_u64 v[58:59], v[56:57], 0, v[4:5]
	v_lshl_add_u64 v[60:61], v[54:55], 0, v[4:5]
	v_or_b32_e32 v4, 32, v2
	v_cmp_gt_u32_e64 s[10:11], v4, v3
	v_or_b32_e32 v4, 33, v2
	v_cmp_gt_u32_e64 s[14:15], v4, v3
	v_or_b32_e32 v4, 2, v2
	v_cmp_gt_u32_e64 s[16:17], v4, v3
	v_or_b32_e32 v4, 34, v2
	v_cmp_gt_u32_e64 s[18:19], v4, v3
	v_or_b32_e32 v4, 3, v2
	v_cmp_gt_u32_e64 s[20:21], v4, v3
	v_or_b32_e32 v4, 35, v2
	v_cmp_gt_u32_e64 s[22:23], v4, v3
	v_or_b32_e32 v4, 8, v2
	s_mov_b64 s[2:3], 0x4000
	v_cmp_gt_u32_e64 s[24:25], v4, v3
	v_or_b32_e32 v4, 40, v2
	v_cmp_gt_u32_e64 s[26:27], v4, v3
	v_or_b32_e32 v4, 9, v2
	v_cmp_gt_u32_e64 s[28:29], v4, v3
	v_or_b32_e32 v4, 41, v2
	v_cmp_gt_u32_e64 s[30:31], v4, v3
	v_or_b32_e32 v4, 10, v2
	v_cmp_gt_u32_e64 s[34:35], v4, v3
	v_or_b32_e32 v4, 42, v2
	v_cmp_gt_u32_e64 s[36:37], v4, v3
	v_or_b32_e32 v4, 11, v2
	v_cmp_gt_u32_e64 s[38:39], v4, v3
	v_or_b32_e32 v4, 43, v2
	v_cmp_gt_u32_e64 s[40:41], v4, v3
	s_waitcnt vmcnt(0)
; #define LAS __attribute__((address_space(3)))
; __device__ __forceinline__ float bflo(unsigned w) { return __uint_as_float(w << 16); }
; __device__ __forceinline__ float bfhi(unsigned w) { return __uint_as_float(w & 0xffff0000u); }
; #define ATT_WAIT_BAR() asm volatile("s_waitcnt vmcnt(0) lgkmcnt(0)\n\ts_barrier" ::: "memory")
; template <int TYPE>
; __device__ __forceinline__ void conv_store(const ConvRegs& c, const Args& a, int l, int h, size_t rowq, int lane) {
; #pragma unroll
;     for (int i = 0; i < 4; ++i) { const size_t grow = rowq + i * 8 + (lane >> 3);
;         float* ko = a.out + (TYPE == 0 ? O_FKP : O_SKP) + ((size_t)l * MP + grow) * W + h * HD + (lane & 7) * 8;
;         float* vo = a.out + (TYPE == 0 ? O_FVP : O_SVP) + ((size_t)l * MP + grow) * W + h * HD + (lane & 7) * 8;
;         const u32x4 kw = c.k[i], vw = c.v[i];
;         __builtin_nontemporal_store((f32x4){bflo(kw.x), bfhi(kw.x), bflo(kw.y), bfhi(kw.y)}, (f32x4*)ko); __builtin_nontemporal_store((f32x4){bflo(kw.z), bfhi(kw.z), bflo(kw.w), bfhi(kw.w)}, (f32x4*)(ko + 4));
;         __builtin_nontemporal_store((f32x4){bflo(vw.x), bfhi(vw.x), bflo(vw.y), bfhi(vw.y)}, (f32x4*)vo); __builtin_nontemporal_store((f32x4){bflo(vw.z), bfhi(vw.z), bflo(vw.w), bfhi(vw.w)}, (f32x4*)(vo + 4)); }
; }
; __device__ __forceinline__ void prompt_unit_fox(const Args& a, int l, int b, int h, int qb, LAS unsigned char* lds) {
;     ...
;     const lds_cptr vp0 = (lds_cptr)lds + F_V + ((lane >> 4) & 1) * 32 + (lane & 3) * 8 + (4 * hi + ((lane & 15) >> 2)) * 64;
;     const int ql = 32 * (wid & 1) + r32, qlim = ql + 1;
;     LAS float* wsf = (LAS float*)(lds + F_WSF) + wid * 64;
;     FoxState st; st.m = 0.f; st.l = 0.f; st.mq = (bf16x8){}; st.o[0] = (f32x16){}; st.o[1] = (f32x16){};
;     PairP pp; bool pending = false;
; #pragma unroll
;     for (int i = 0; i < 8; ++i) pp.w[i] = (u32x4){0u, 0u, 0u, 0u};
;     { ConvRegs cv; conv_load(cv, a, rowb + q0 + wid * 32, col, lane); conv_store<0>(cv, a, l, h, rowb + q0 + wid * 32, lane); }
;     int slot = 0, pslot = 0;
;     ...
;         ATT_WAIT_BAR();
	v_lshlrev_b32_e32 v54, 16, v22
	v_and_b32_e32 v55, 0xffff0000, v22
	v_lshlrev_b32_e32 v56, 16, v23
	v_and_b32_e32 v57, 0xffff0000, v23
	v_lshlrev_b32_e32 v22, 16, v24
	v_and_b32_e32 v23, 0xffff0000, v24
	v_lshlrev_b32_e32 v24, 16, v25
	v_and_b32_e32 v25, 0xffff0000, v25
	global_store_dwordx4 v[58:59], v[22:25], off offset:16
	v_or_b32_e32 v4, 16, v2
	v_cmp_gt_u32_e64 s[42:43], v4, v3
	v_lshlrev_b32_e32 v22, 16, v26
	v_and_b32_e32 v23, 0xffff0000, v26
	v_lshlrev_b32_e32 v24, 16, v27
	v_and_b32_e32 v25, 0xffff0000, v27
	global_store_dwordx4 v[60:61], v[22:25], off
	v_lshl_add_u64 v[26:27], v[58:59], 0, s[2:3]
	v_or_b32_e32 v4, 48, v2
	v_lshlrev_b32_e32 v22, 16, v28
	v_and_b32_e32 v23, 0xffff0000, v28
	v_lshlrev_b32_e32 v24, 16, v29
	v_and_b32_e32 v25, 0xffff0000, v29
	v_lshl_add_u64 v[28:29], v[60:61], 0, s[2:3]
	s_movk_i32 s2, 0x4000
	global_store_dwordx4 v[60:61], v[22:25], off offset:16
	v_cmp_gt_u32_e64 s[44:45], v4, v3
	v_or_b32_e32 v4, 17, v2
	v_lshlrev_b32_e32 v22, 16, v30
	v_and_b32_e32 v23, 0xffff0000, v30
	v_add_co_u32_e32 v30, vcc, s2, v58
	v_lshlrev_b32_e32 v24, 16, v31
	v_and_b32_e32 v25, 0xffff0000, v31
	v_addc_co_u32_e32 v31, vcc, 0, v59, vcc
	global_store_dwordx4 v[30:31], v[22:25], off
	v_cmp_gt_u32_e64 s[46:47], v4, v3
	v_or_b32_e32 v4, 49, v2
	v_lshlrev_b32_e32 v22, 16, v32
	v_and_b32_e32 v23, 0xffff0000, v32
	v_lshlrev_b32_e32 v24, 16, v33
	v_and_b32_e32 v25, 0xffff0000, v33
	global_store_dwordx4 v[26:27], v[22:25], off offset:16
	v_add_co_u32_e32 v26, vcc, s2, v60
	s_nop 0
	v_lshlrev_b32_e32 v22, 16, v34
	v_and_b32_e32 v23, 0xffff0000, v34
	v_lshlrev_b32_e32 v24, 16, v35
	v_and_b32_e32 v25, 0xffff0000, v35
	v_addc_co_u32_e32 v27, vcc, 0, v61, vcc
	global_store_dwordx4 v[26:27], v[22:25], off
	s_mov_b64 s[2:3], 0x8000
	v_lshl_add_u64 v[26:27], v[58:59], 0, s[2:3]
	v_lshlrev_b32_e32 v22, 16, v36
	v_and_b32_e32 v23, 0xffff0000, v36
	v_lshlrev_b32_e32 v24, 16, v37
	v_and_b32_e32 v25, 0xffff0000, v37
	global_store_dwordx4 v[28:29], v[22:25], off offset:16
	v_lshl_add_u64 v[28:29], v[60:61], 0, s[2:3]
	s_mov_b32 s2, 0x8000
	v_add_co_u32_e32 v30, vcc, s2, v58
	v_lshlrev_b32_e32 v22, 16, v38
	v_and_b32_e32 v23, 0xffff0000, v38
	v_lshlrev_b32_e32 v24, 16, v39
	v_and_b32_e32 v25, 0xffff0000, v39
	v_addc_co_u32_e32 v31, vcc, 0, v59, vcc
	global_store_dwordx4 v[30:31], v[22:25], off
	v_cmp_gt_u32_e64 s[48:49], v4, v3
	v_or_b32_e32 v4, 18, v2
	v_lshlrev_b32_e32 v22, 16, v40
	v_and_b32_e32 v23, 0xffff0000, v40
	v_lshlrev_b32_e32 v24, 16, v41
	v_and_b32_e32 v25, 0xffff0000, v41
	global_store_dwordx4 v[26:27], v[22:25], off offset:16
	v_add_co_u32_e32 v26, vcc, s2, v60
	v_cmp_gt_u32_e64 s[50:51], v4, v3
	v_or_b32_e32 v4, 50, v2
	v_lshlrev_b32_e32 v22, 16, v42
	v_and_b32_e32 v23, 0xffff0000, v42
	v_lshlrev_b32_e32 v24, 16, v43
	v_and_b32_e32 v25, 0xffff0000, v43
	v_addc_co_u32_e32 v27, vcc, 0, v61, vcc
	v_cmp_gt_u32_e64 s[52:53], v4, v3
	v_or_b32_e32 v4, 19, v2
	global_store_dwordx4 v[26:27], v[22:25], off
	s_mov_b64 s[2:3], 0xc000
	v_cmp_gt_u32_e64 s[54:55], v4, v3
	v_lshlrev_b32_e32 v22, 16, v44
	v_and_b32_e32 v23, 0xffff0000, v44
	v_lshlrev_b32_e32 v24, 16, v45
	v_and_b32_e32 v25, 0xffff0000, v45
	v_or_b32_e32 v4, 51, v2
	global_store_dwordx4 v[28:29], v[22:25], off offset:16
	v_lshl_add_u64 v[26:27], v[58:59], 0, s[2:3]
	v_lshl_add_u64 v[28:29], v[60:61], 0, s[2:3]
	s_mov_b32 s2, 0xc000
	v_cmp_gt_u32_e64 s[56:57], v4, v3
	v_or_b32_e32 v4, 24, v2
	v_add_co_u32_e32 v30, vcc, s2, v58
	v_cmp_gt_u32_e64 s[58:59], v4, v3
	v_or_b32_e32 v4, 56, v2
	v_lshlrev_b32_e32 v22, 16, v46
	v_and_b32_e32 v23, 0xffff0000, v46
	v_lshlrev_b32_e32 v24, 16, v47
	v_and_b32_e32 v25, 0xffff0000, v47
	v_addc_co_u32_e32 v31, vcc, 0, v59, vcc
	v_cmp_gt_u32_e64 s[60:61], v4, v3
	v_or_b32_e32 v4, 25, v2
	global_store_dwordx4 v[30:31], v[22:25], off
	v_cmp_gt_u32_e64 s[62:63], v4, v3
	v_or_b32_e32 v4, 57, v2
	v_lshlrev_b32_e32 v22, 16, v48
	v_and_b32_e32 v23, 0xffff0000, v48
	v_lshlrev_b32_e32 v24, 16, v49
	v_and_b32_e32 v25, 0xffff0000, v49
	global_store_dwordx4 v[26:27], v[22:25], off offset:16
	v_add_co_u32_e32 v26, vcc, s2, v60
	s_add_i32 s2, 0, 0x18000
	v_cmp_gt_u32_e64 s[64:65], v4, v3
	v_or_b32_e32 v4, 26, v2
	v_lshlrev_b32_e32 v22, 16, v50
	v_and_b32_e32 v23, 0xffff0000, v50
	v_lshlrev_b32_e32 v24, 16, v51
	v_and_b32_e32 v25, 0xffff0000, v51
	v_addc_co_u32_e32 v27, vcc, 0, v61, vcc
	v_add_u32_e32 v186, s2, v174
	s_add_i32 s2, 0, 0x1a800
	v_cmp_gt_u32_e64 s[66:67], v4, v3
	v_or_b32_e32 v4, 58, v2
	v_mov_b32_e32 v66, v5
	v_mov_b32_e32 v67, v5
	global_store_dwordx4 v[58:59], v[54:57], off
	global_store_dwordx4 v[26:27], v[22:25], off
	s_bitcmp1_b32 s6, 7
	v_cmp_gt_u32_e64 s[6:7], 32, v20
	v_lshlrev_b32_e32 v22, 16, v52
	v_and_b32_e32 v23, 0xffff0000, v52
	v_lshlrev_b32_e32 v24, 16, v53
	v_and_b32_e32 v25, 0xffff0000, v53
	v_cmp_gt_u32_e64 s[8:9], v2, v3
	v_cmp_lt_u32_e64 s[12:13], v2, v3
	v_cmp_gt_u32_e64 s[68:69], v4, v3
	v_or_b32_e32 v4, 27, v2
	v_or_b32_e32 v2, 59, v2
	v_mov_b32_e32 v52, v5
	v_mov_b32_e32 v53, v5
	v_mov_b32_e32 v54, v5
	v_mov_b32_e32 v55, v5
	v_mov_b32_e32 v56, v5
	v_mov_b32_e32 v57, v5
	v_mov_b32_e32 v58, v5
	v_mov_b32_e32 v59, v5
	v_mov_b32_e32 v60, v5
	v_mov_b32_e32 v61, v5
	v_mov_b32_e32 v62, v5
	v_mov_b32_e32 v63, v5
	v_mov_b32_e32 v64, v5
	v_mov_b32_e32 v65, v5
	v_mov_b64_e32 v[82:83], v[66:67]
	s_mov_b32 s75, 0
	v_lshl_add_u32 v188, v180, 3, s2
	s_cselect_b64 s[94:95], -1, 0
	v_lshlrev_b32_e32 v182, 10, v21
	v_lshlrev_b32_e32 v189, 4, v180
	v_cndmask_b32_e64 v122, 0, v183, s[6:7]
	v_cndmask_b32_e64 v121, 0, -1.0, s[6:7]
	v_mov_b32_e32 v120, v5
	v_mov_b32_e32 v123, v5
	v_cmp_gt_u32_e64 s[70:71], v4, v3
	v_cmp_gt_u32_e64 s[72:73], v2, v3
	v_lshl_add_u32 v184, v180, 2, s89
	v_mov_b32_e32 v156, v5
	v_mov_b32_e32 v157, v5
	v_mov_b32_e32 v158, v5
	v_mov_b32_e32 v159, v5
	v_mov_b32_e32 v192, 0
	s_mov_b64 s[2:3], 0
	v_mov_b32_e32 v124, 0
	v_mov_b32_e32 v125, 0
	v_mov_b32_e32 v126, 0
	v_mov_b32_e32 v127, 0
	v_mov_b32_e32 v128, 0
	v_mov_b32_e32 v129, 0
	v_mov_b32_e32 v130, 0
	v_mov_b32_e32 v131, 0
	v_mov_b32_e32 v132, 0
	v_mov_b32_e32 v133, 0
	v_mov_b32_e32 v134, 0
	v_mov_b32_e32 v135, 0
	v_mov_b32_e32 v136, 0
	v_mov_b32_e32 v137, 0
	v_mov_b32_e32 v138, 0
	v_mov_b32_e32 v139, 0
	v_mov_b32_e32 v140, 0
	v_mov_b32_e32 v141, 0
	v_mov_b32_e32 v142, 0
	v_mov_b32_e32 v143, 0
	v_mov_b32_e32 v144, 0
	v_mov_b32_e32 v145, 0
	v_mov_b32_e32 v146, 0
	v_mov_b32_e32 v147, 0
	v_mov_b32_e32 v148, 0
	v_mov_b32_e32 v149, 0
	v_mov_b32_e32 v150, 0
	v_mov_b32_e32 v151, 0
	v_mov_b32_e32 v152, 0
	v_mov_b32_e32 v153, 0
	v_mov_b32_e32 v154, 0
	v_mov_b32_e32 v155, 0
	v_cndmask_b32_e64 v2, 0, v185, s[6:7]
	s_mov_b32 s93, 0
	v_mov_b64_e32 v[80:81], v[64:65]
	v_mov_b64_e32 v[78:79], v[62:63]
	v_mov_b64_e32 v[76:77], v[60:61]
	v_mov_b64_e32 v[74:75], v[58:59]
	v_mov_b64_e32 v[72:73], v[56:57]
	v_mov_b64_e32 v[70:71], v[54:55]
	v_mov_b64_e32 v[68:69], v[52:53]
	v_mov_b32_e32 v193, 0
	global_store_dwordx4 v[28:29], v[22:25], off offset:16
	s_waitcnt vmcnt(16) lgkmcnt(0)
	s_barrier
	s_branch .Lfox_top_l1

; __device__ __forceinline__ void pv(f32x16 (&o)[2], const VFrags& v, const u32x4& pw0, const u32x4& pw1, const u32x4& pw2, const u32x4& pw3) {
;     ...
;     o[0] = __builtin_amdgcn_mfma_f32_32x32x16_bf16(__builtin_bit_cast(bf16x8, pw0), ATT_VF(0), o[0], 0, 0, 0);
;     o[1] = __builtin_amdgcn_mfma_f32_32x32x16_bf16(__builtin_bit_cast(bf16x8, pw0), ATT_VF(4), o[1], 0, 0, 0);
;     o[0] = __builtin_amdgcn_mfma_f32_32x32x16_bf16(__builtin_bit_cast(bf16x8, pw1), ATT_VF(1), o[0], 0, 0, 0);
;     o[1] = __builtin_amdgcn_mfma_f32_32x32x16_bf16(__builtin_bit_cast(bf16x8, pw1), ATT_VF(5), o[1], 0, 0, 0);
;     o[0] = __builtin_amdgcn_mfma_f32_32x32x16_bf16(__builtin_bit_cast(bf16x8, pw2), ATT_VF(2), o[0], 0, 0, 0);
;     o[1] = __builtin_amdgcn_mfma_f32_32x32x16_bf16(__builtin_bit_cast(bf16x8, pw2), ATT_VF(6), o[1], 0, 0, 0);
;     o[0] = __builtin_amdgcn_mfma_f32_32x32x16_bf16(__builtin_bit_cast(bf16x8, pw3), ATT_VF(3), o[0], 0, 0, 0);
;     o[1] = __builtin_amdgcn_mfma_f32_32x32x16_bf16(__builtin_bit_cast(bf16x8, pw3), ATT_VF(7), o[1], 0, 0, 0);
;     ...
; }
; __device__ __forceinline__ void fox_pair_pv(FoxState& st, const PairP& pp, lds_cptr vpB) {
;     { VFrags vf; vfrags(vf, vpB + 8192); pv(st.o, vf, pp.w[0], pp.w[1], pp.w[2], pp.w[3]); }
;     { VFrags vf; vfrags(vf, vpB); pv(st.o, vf, pp.w[4], pp.w[5], pp.w[6], pp.w[7]); }
; }
.LBB0_967:
	s_andn2_b64 vcc, exec, s[2:3]
	s_cbranch_vccnz .LBB0_969
	v_lshl_add_u32 v3, s75, 14, v175
	ds_read_b64_tr_b16 v[84:85], v3 offset:57344
	ds_read_b64_tr_b16 v[86:87], v3 offset:57856
	ds_read_b64_tr_b16 v[88:89], v3 offset:61440
	ds_read_b64_tr_b16 v[90:91], v3 offset:61952
	ds_read_b64_tr_b16 v[92:93], v3 offset:58368
	ds_read_b64_tr_b16 v[94:95], v3 offset:58880
	ds_read_b64_tr_b16 v[96:97], v3 offset:62464
	ds_read_b64_tr_b16 v[98:99], v3 offset:62976
	ds_read_b64_tr_b16 v[100:101], v3 offset:59392
	ds_read_b64_tr_b16 v[102:103], v3 offset:59904
	ds_read_b64_tr_b16 v[104:105], v3 offset:63488
	ds_read_b64_tr_b16 v[106:107], v3 offset:64000
	ds_read_b64_tr_b16 v[108:109], v3 offset:60416
	ds_read_b64_tr_b16 v[110:111], v3 offset:60928
	s_waitcnt lgkmcnt(12)
	v_mfma_f32_32x32x16_bf16 v[68:83], v[152:155], v[84:87], v[68:83]
	ds_read_b64_tr_b16 v[112:113], v3 offset:64512
	ds_read_b64_tr_b16 v[114:115], v3 offset:65024
	s_waitcnt lgkmcnt(12)
	v_mfma_f32_32x32x16_bf16 v[52:67], v[152:155], v[88:91], v[52:67]
	ds_read_b64_tr_b16 v[84:85], v3 offset:49152
	ds_read_b64_tr_b16 v[86:87], v3 offset:49664
	s_waitcnt lgkmcnt(12)
	v_mfma_f32_32x32x16_bf16 v[68:83], v[148:151], v[92:95], v[68:83]
	ds_read_b64_tr_b16 v[88:89], v3 offset:53248
	ds_read_b64_tr_b16 v[90:91], v3 offset:53760
	s_waitcnt lgkmcnt(12)
	v_mfma_f32_32x32x16_bf16 v[52:67], v[148:151], v[96:99], v[52:67]
	ds_read_b64_tr_b16 v[92:93], v3 offset:50176
	ds_read_b64_tr_b16 v[94:95], v3 offset:50688
	s_waitcnt lgkmcnt(12)
	v_mfma_f32_32x32x16_bf16 v[68:83], v[144:147], v[100:103], v[68:83]
	ds_read_b64_tr_b16 v[96:97], v3 offset:54272
	ds_read_b64_tr_b16 v[98:99], v3 offset:54784
	s_waitcnt lgkmcnt(12)
	v_mfma_f32_32x32x16_bf16 v[52:67], v[144:147], v[104:107], v[52:67]
	ds_read_b64_tr_b16 v[100:101], v3 offset:51200
	ds_read_b64_tr_b16 v[102:103], v3 offset:51712
	s_waitcnt lgkmcnt(12)
	v_mfma_f32_32x32x16_bf16 v[68:83], v[140:143], v[108:111], v[68:83]
	ds_read_b64_tr_b16 v[104:105], v3 offset:55296
	ds_read_b64_tr_b16 v[106:107], v3 offset:55808
	s_waitcnt lgkmcnt(12)
	v_mfma_f32_32x32x16_bf16 v[52:67], v[140:143], v[112:115], v[52:67]
	ds_read_b64_tr_b16 v[108:109], v3 offset:52224
	ds_read_b64_tr_b16 v[110:111], v3 offset:52736
	s_waitcnt lgkmcnt(12)
	v_mfma_f32_32x32x16_bf16 v[68:83], v[136:139], v[84:87], v[68:83]
	ds_read_b64_tr_b16 v[112:113], v3 offset:56320
	ds_read_b64_tr_b16 v[114:115], v3 offset:56832
	s_waitcnt lgkmcnt(12)
	v_mfma_f32_32x32x16_bf16 v[52:67], v[136:139], v[88:91], v[52:67]
	s_waitcnt lgkmcnt(10)
	v_mfma_f32_32x32x16_bf16 v[68:83], v[132:135], v[92:95], v[68:83]
	s_waitcnt lgkmcnt(8)
	v_mfma_f32_32x32x16_bf16 v[52:67], v[132:135], v[96:99], v[52:67]
	s_waitcnt lgkmcnt(6)
	v_mfma_f32_32x32x16_bf16 v[68:83], v[128:131], v[100:103], v[68:83]
	s_waitcnt lgkmcnt(4)
	v_mfma_f32_32x32x16_bf16 v[52:67], v[128:131], v[104:107], v[52:67]
	s_waitcnt lgkmcnt(2)
	v_mfma_f32_32x32x16_bf16 v[68:83], v[124:127], v[108:111], v[68:83]
	s_waitcnt lgkmcnt(0)
	v_mfma_f32_32x32x16_bf16 v[52:67], v[124:127], v[112:115], v[52:67]

; #define LAS __attribute__((address_space(3)))
; __device__ __forceinline__ bool fox_pair_qs(FoxState& st, PairP& pp, lds_cptr kslotB, const bf16x8 (&qr)[4], const LAS u32x2* augB  , bool careful, int r32, int hi, LAS float* wsf) {
;     bf16x8 kfA[8], kfB[8]; kfrags(kfA, kslotB + 8192, r32, hi); kfrags(kfB, kslotB, r32, hi);
;     const u32x2 t0 = augB[64], t1 = augB[96], t2 = augB[0], t3 = augB[32];
;     const f32x16 zz = {};
;     f32x16 a0, a1, b0, b1;
;     a0 = __builtin_amdgcn_mfma_f32_32x32x16_bf16(__builtin_bit_cast(bf16x8, (u32x4){t0.x, t0.y, 0xBF80BF80u, 0u}), st.mq, zz, 0, 0, 0);
;     a1 = __builtin_amdgcn_mfma_f32_32x32x16_bf16(__builtin_bit_cast(bf16x8, (u32x4){t1.x, t1.y, 0xBF80BF80u, 0u}), st.mq, zz, 0, 0, 0);
;     b0 = __builtin_amdgcn_mfma_f32_32x32x16_bf16(__builtin_bit_cast(bf16x8, (u32x4){t2.x, t2.y, 0xBF80BF80u, 0u}), st.mq, zz, 0, 0, 0);
;     b1 = __builtin_amdgcn_mfma_f32_32x32x16_bf16(__builtin_bit_cast(bf16x8, (u32x4){t3.x, t3.y, 0xBF80BF80u, 0u}), st.mq, zz, 0, 0, 0);
; #pragma unroll
;     for (int d0 = 0; d0 < 4; ++d0) {
;         a0 = __builtin_amdgcn_mfma_f32_32x32x16_bf16(kfA[2 * d0], qr[d0], a0, 0, 0, 0); a1 = __builtin_amdgcn_mfma_f32_32x32x16_bf16(kfA[2 * d0 + 1], qr[d0], a1, 0, 0, 0);
;         b0 = __builtin_amdgcn_mfma_f32_32x32x16_bf16(kfB[2 * d0], qr[d0], b0, 0, 0, 0); b1 = __builtin_amdgcn_mfma_f32_32x32x16_bf16(kfB[2 * d0 + 1], qr[d0], b1, 0, 0, 0);
;     }
.LBB0_982:
	ds_read_b64 v[56:57], v124 offset:512
	ds_read_b64 v[60:61], v124 offset:768
	ds_read_b64 v[52:53], v124
	ds_read_b64 v[70:71], v124 offset:256
	ds_read_b128 v[196:199], v125 offset:8192
	ds_read_b128 v[200:203], v125 offset:8704
	ds_read_b128 v[204:207], v125
	ds_read_b128 v[208:211], v125 offset:512
	ds_read_b128 v[220:223], v125 offset:10240
	ds_read_b128 v[224:227], v125 offset:10752
	ds_read_b128 v[228:231], v125 offset:2048
	ds_read_b128 v[232:235], v125 offset:2560
	v_mov_b64_e32 v[58:59], s[86:87]
	v_mov_b64_e32 v[62:63], s[86:87]
	v_mov_b64_e32 v[54:55], s[86:87]
	v_mov_b64_e32 v[72:73], s[86:87]
	s_xor_b64 s[2:3], s[82:83], -1
	s_and_b64 vcc, exec, s[2:3]
	s_waitcnt lgkmcnt(11)
	v_mfma_f32_32x32x16_bf16 v[84:99], v[56:59], v[160:163], 0
	s_waitcnt lgkmcnt(10)
	v_mfma_f32_32x32x16_bf16 v[100:115], v[60:63], v[160:163], 0
	s_waitcnt lgkmcnt(9)
	v_mfma_f32_32x32x16_bf16 v[52:67], v[52:55], v[160:163], 0
	s_waitcnt lgkmcnt(8)
	v_mfma_f32_32x32x16_bf16 v[68:83], v[70:73], v[160:163], 0
	s_waitcnt lgkmcnt(7)
	v_mfma_f32_32x32x16_bf16 v[84:99], v[196:199], v[6:9], v[84:99]
	ds_read_b128 v[196:199], v125 offset:12288
	s_waitcnt lgkmcnt(7)
	v_mfma_f32_32x32x16_bf16 v[100:115], v[200:203], v[6:9], v[100:115]
	ds_read_b128 v[200:203], v125 offset:12800
	s_waitcnt lgkmcnt(7)
	v_mfma_f32_32x32x16_bf16 v[52:67], v[204:207], v[6:9], v[52:67]
	ds_read_b128 v[204:207], v125 offset:4096
	s_waitcnt lgkmcnt(7)
	v_mfma_f32_32x32x16_bf16 v[68:83], v[208:211], v[6:9], v[68:83]
	ds_read_b128 v[208:211], v125 offset:4608
	s_waitcnt lgkmcnt(7)
	v_mfma_f32_32x32x16_bf16 v[84:99], v[220:223], v[10:13], v[84:99]
	ds_read_b128 v[220:223], v125 offset:14336
	s_waitcnt lgkmcnt(7)
	v_mfma_f32_32x32x16_bf16 v[100:115], v[224:227], v[10:13], v[100:115]
	ds_read_b128 v[224:227], v125 offset:14848
	s_waitcnt lgkmcnt(7)
	v_mfma_f32_32x32x16_bf16 v[52:67], v[228:231], v[10:13], v[52:67]
	ds_read_b128 v[228:231], v125 offset:6144
	s_waitcnt lgkmcnt(7)
	v_mfma_f32_32x32x16_bf16 v[68:83], v[232:235], v[10:13], v[68:83]
	ds_read_b128 v[232:235], v125 offset:6656
	s_waitcnt lgkmcnt(7)
	v_mfma_f32_32x32x16_bf16 v[84:99], v[196:199], v[14:17], v[84:99]
	s_waitcnt lgkmcnt(6)
	v_mfma_f32_32x32x16_bf16 v[100:115], v[200:203], v[14:17], v[100:115]
	s_waitcnt lgkmcnt(5)
	v_mfma_f32_32x32x16_bf16 v[52:67], v[204:207], v[14:17], v[52:67]
	s_waitcnt lgkmcnt(4)
	v_mfma_f32_32x32x16_bf16 v[68:83], v[208:211], v[14:17], v[68:83]
	s_waitcnt lgkmcnt(3)
	v_mfma_f32_32x32x16_bf16 v[84:99], v[220:223], v[116:119], v[84:99]
	s_waitcnt lgkmcnt(2)
	v_mfma_f32_32x32x16_bf16 v[100:115], v[224:227], v[116:119], v[100:115]
	s_waitcnt lgkmcnt(1)
	v_mfma_f32_32x32x16_bf16 v[52:67], v[228:231], v[116:119], v[52:67]
	s_waitcnt lgkmcnt(0)
	v_mfma_f32_32x32x16_bf16 v[68:83], v[232:235], v[116:119], v[68:83]
	s_nop 2
	s_cbranch_vccnz .LBB0_986
; #define LAS __attribute__((address_space(3)))
; __device__ __forceinline__ float swap_max(float m) { auto rr = __builtin_amdgcn_permlane32_swap(__float_as_uint(m), __float_as_uint(m), false, false); return fmaxf(__uint_as_float(rr[0]), __uint_as_float(rr[1])); }
; __device__ __forceinline__ float max3f(float a, float b, float c) { return __builtin_fmaxf(__builtin_fmaxf(a, b), c); }
; #define ATT_LDS_WAIT() asm volatile("s_waitcnt lgkmcnt(0)" ::: "memory")
; __device__ __forceinline__ bool fox_pair_qs(FoxState& st, PairP& pp, lds_cptr kslotB, const bf16x8 (&qr)[4], const LAS u32x2* augB  , bool careful, int r32, int hi, LAS float* wsf) {
;     ...
;     if (careful) {
;         asm volatile("; careful pass: move the reference" ::: "memory");
;         float rm = max3f(a0[0], a1[0], b0[0]), rm2 = max3f(b1[0], a0[1], a1[1]);
;         rm = max3f(rm, b0[1], b1[1]);
; #pragma unroll
;         for (int r = 2; r < 16; ++r) { rm = max3f(rm, a0[r], a1[r]); rm2 = max3f(rm2, b0[r], b1[r]); }
;         rm = swap_max(max3f(rm, rm2, rm2));
;         const float dl = fmaxf(rm, 0.f);
;         st.m += dl; st.mq = make_mq(st.m, hi);
; #pragma unroll
;         for (int r = 0; r < 16; ++r) { a0[r] -= dl; a1[r] -= dl; b0[r] -= dl; b1[r] -= dl; }
;         const float f = __builtin_amdgcn_exp2f(-dl);
;         st.l *= f;
;         if (hi == 0) wsf[r32] = f;
;         ATT_LDS_WAIT();
; #pragma unroll
;         for (int g = 0; g < 4; ++g) { const f32x4 fv = *(const LAS f32x4*)(wsf + 8 * g + 4 * hi);
; #pragma unroll
;             for (int i = 0; i < 4; ++i) { st.o[0][4 * g + i] *= fv[i]; st.o[1][4 * g + i] *= fv[i]; } }
;     }
	s_nop 4
	v_max_f32_e32 v3, v100, v100
	v_max_f32_e32 v4, v84, v84
	v_max_f32_e32 v3, v4, v3
	s_nop 2
	v_max3_f32 v4, v68, v85, v101
	v_max3_f32 v3, v3, v52, v53
	v_max3_f32 v3, v3, v69, v86
	v_max3_f32 v4, v4, v54, v70
	v_max3_f32 v3, v3, v102, v87
	v_max3_f32 v4, v4, v55, v71
	v_max3_f32 v3, v3, v103, v88
	v_max3_f32 v4, v4, v56, v72
	v_max3_f32 v3, v3, v104, v89
	v_max3_f32 v4, v4, v57, v73
	v_max3_f32 v3, v3, v105, v90
	v_max3_f32 v4, v4, v58, v74
	v_max3_f32 v3, v3, v106, v91
	v_max3_f32 v4, v4, v59, v75
	v_max3_f32 v3, v3, v107, v92
	v_max3_f32 v4, v4, v60, v76
	v_max3_f32 v3, v3, v108, v93
	v_max3_f32 v4, v4, v61, v77
	v_max3_f32 v3, v3, v109, v94
	v_max3_f32 v4, v4, v62, v78
	v_max3_f32 v3, v3, v110, v95
	v_max3_f32 v4, v4, v63, v79
	v_max3_f32 v3, v3, v111, v96
	v_max3_f32 v4, v4, v64, v80
	v_max3_f32 v3, v3, v112, v97
	v_max3_f32 v4, v4, v65, v81
	v_max3_f32 v3, v3, v113, v98
	v_max3_f32 v4, v4, v66, v82
	v_max3_f32 v3, v3, v114, v99
	v_max3_f32 v4, v4, v67, v83
	v_max3_f32 v3, v3, v115, v4
	v_mov_b32_e32 v4, v3
	s_nop 1
	v_permlane32_swap_b32_e32 v3, v4
	v_max3_f32 v126, v3, v4, 0
	v_exp_f32_e64 v127, -v126
	s_and_saveexec_b64 vcc, s[6:7]
	ds_write_b32 v184, v127
	s_or_b64 exec, exec, vcc
	v_add_f32_e32 v191, v191, v126
	v_cvt_pk_bf16_f32 v3, v191, 0
	v_lshlrev_b32_e32 v3, 16, v3
	v_sub_f32_e32 v4, v191, v3
	v_cvt_pk_bf16_f32 v128, v4, 0
	v_lshlrev_b32_e32 v128, 16, v128
	v_sub_f32_e32 v4, v4, v128
	s_waitcnt lgkmcnt(0)
	v_add_u32_e32 v138, s89, v174
	v_cvt_pk_bf16_f32 v4, v128, v4
	v_sub_f32_e32 v99, v99, v126
	v_sub_f32_e32 v98, v98, v126
	v_sub_f32_e32 v97, v97, v126
	v_sub_f32_e32 v96, v96, v126
	v_sub_f32_e32 v95, v95, v126
	v_sub_f32_e32 v94, v94, v126
	v_sub_f32_e32 v93, v93, v126
	v_sub_f32_e32 v92, v92, v126
	v_sub_f32_e32 v91, v91, v126
	v_sub_f32_e32 v90, v90, v126
	v_sub_f32_e32 v89, v89, v126
	v_sub_f32_e32 v88, v88, v126
	v_sub_f32_e32 v87, v87, v126
	v_sub_f32_e32 v86, v86, v126
	v_sub_f32_e32 v85, v85, v126
	v_sub_f32_e32 v84, v84, v126
	v_sub_f32_e32 v115, v115, v126
	v_sub_f32_e32 v114, v114, v126
	v_sub_f32_e32 v113, v113, v126
	v_sub_f32_e32 v112, v112, v126
	v_sub_f32_e32 v111, v111, v126
	v_sub_f32_e32 v110, v110, v126
	v_sub_f32_e32 v109, v109, v126
	v_sub_f32_e32 v108, v108, v126
	v_sub_f32_e32 v107, v107, v126
	v_sub_f32_e32 v106, v106, v126
	v_sub_f32_e32 v105, v105, v126
	v_sub_f32_e32 v104, v104, v126
	v_sub_f32_e32 v103, v103, v126
	v_sub_f32_e32 v102, v102, v126
	v_sub_f32_e32 v101, v101, v126
	v_sub_f32_e32 v100, v100, v126
	v_sub_f32_e32 v67, v67, v126
	v_sub_f32_e32 v66, v66, v126
	v_sub_f32_e32 v65, v65, v126
	v_sub_f32_e32 v64, v64, v126
	v_sub_f32_e32 v63, v63, v126
	v_sub_f32_e32 v62, v62, v126
	v_sub_f32_e32 v61, v61, v126
	v_sub_f32_e32 v60, v60, v126
	v_sub_f32_e32 v59, v59, v126
	v_sub_f32_e32 v58, v58, v126
	v_sub_f32_e32 v57, v57, v126
	v_sub_f32_e32 v56, v56, v126
	v_sub_f32_e32 v55, v55, v126
	v_sub_f32_e32 v54, v54, v126
	v_sub_f32_e32 v53, v53, v126
	v_sub_f32_e32 v52, v52, v126
	v_sub_f32_e32 v83, v83, v126
	v_sub_f32_e32 v82, v82, v126
	v_sub_f32_e32 v81, v81, v126
	v_sub_f32_e32 v80, v80, v126
	v_sub_f32_e32 v79, v79, v126
	v_sub_f32_e32 v78, v78, v126
	v_sub_f32_e32 v77, v77, v126
	v_sub_f32_e32 v76, v76, v126
	v_sub_f32_e32 v75, v75, v126
	v_sub_f32_e32 v74, v74, v126
	v_sub_f32_e32 v73, v73, v126
	v_sub_f32_e32 v72, v72, v126
	v_sub_f32_e32 v71, v71, v126
	v_sub_f32_e32 v70, v70, v126
	v_sub_f32_e32 v69, v69, v126
	v_sub_f32_e32 v68, v68, v126
	v_mul_f32_e32 v194, v194, v127
	ds_read_b128 v[126:129], v138
	ds_read_b128 v[130:133], v138 offset:32
	ds_read_b128 v[134:137], v138 offset:64
	ds_read_b128 v[138:141], v138 offset:96
	v_cvt_pk_bf16_f32 v3, 1.0, v3
	v_cndmask_b32_e64 v4, 0, v4, s[6:7]
	v_cndmask_b32_e64 v3, 0, v3, s[6:7]
	v_mov_b64_e32 v[162:163], v[4:5]
	s_waitcnt lgkmcnt(0)
	v_pk_mul_f32 v[32:33], v[32:33], v[138:139]
	v_pk_mul_f32 v[28:29], v[28:29], v[134:135]
	v_pk_mul_f32 v[24:25], v[24:25], v[130:131]
	v_pk_mul_f32 v[34:35], v[34:35], v[140:141]
	v_pk_mul_f32 v[30:31], v[30:31], v[136:137]
	v_pk_mul_f32 v[26:27], v[26:27], v[132:133]
	v_pk_mul_f32 v[22:23], v[22:23], v[128:129]
	v_pk_mul_f32 v[20:21], v[20:21], v[126:127]
	v_pk_mul_f32 v[48:49], v[48:49], v[138:139]
	v_pk_mul_f32 v[44:45], v[44:45], v[134:135]
	v_pk_mul_f32 v[40:41], v[40:41], v[130:131]
	v_pk_mul_f32 v[50:51], v[50:51], v[140:141]
	v_pk_mul_f32 v[46:47], v[46:47], v[136:137]
	v_pk_mul_f32 v[42:43], v[42:43], v[132:133]
	v_pk_mul_f32 v[38:39], v[38:39], v[128:129]
	v_pk_mul_f32 v[36:37], v[36:37], v[126:127]
	v_mov_b64_e32 v[160:161], v[2:3]

; __device__ __forceinline__ void pv(f32x16 (&o)[2], const VFrags& v, const u32x4& pw0, const u32x4& pw1, const u32x4& pw2, const u32x4& pw3) {
;     ...
;     o[0] = __builtin_amdgcn_mfma_f32_32x32x16_bf16(__builtin_bit_cast(bf16x8, pw0), ATT_VF(0), o[0], 0, 0, 0);
;     o[1] = __builtin_amdgcn_mfma_f32_32x32x16_bf16(__builtin_bit_cast(bf16x8, pw0), ATT_VF(4), o[1], 0, 0, 0);
;     o[0] = __builtin_amdgcn_mfma_f32_32x32x16_bf16(__builtin_bit_cast(bf16x8, pw1), ATT_VF(1), o[0], 0, 0, 0);
;     o[1] = __builtin_amdgcn_mfma_f32_32x32x16_bf16(__builtin_bit_cast(bf16x8, pw1), ATT_VF(5), o[1], 0, 0, 0);
;     o[0] = __builtin_amdgcn_mfma_f32_32x32x16_bf16(__builtin_bit_cast(bf16x8, pw2), ATT_VF(2), o[0], 0, 0, 0);
;     o[1] = __builtin_amdgcn_mfma_f32_32x32x16_bf16(__builtin_bit_cast(bf16x8, pw2), ATT_VF(6), o[1], 0, 0, 0);
;     o[0] = __builtin_amdgcn_mfma_f32_32x32x16_bf16(__builtin_bit_cast(bf16x8, pw3), ATT_VF(3), o[0], 0, 0, 0);
;     o[1] = __builtin_amdgcn_mfma_f32_32x32x16_bf16(__builtin_bit_cast(bf16x8, pw3), ATT_VF(7), o[1], 0, 0, 0);
;     ...
; }
; __device__ __forceinline__ bool fox_pair_qs(FoxState& st, PairP& pp, lds_cptr kslotB, const bf16x8 (&qr)[4], const LAS u32x2* augB  , bool careful, int r32, int hi, LAS float* wsf) {
;     ...
;     float sacc = 0.f, sacc2 = 0.f;
; #pragma unroll
;     for (int r = 0; r < 16; ++r) { a0[r] = __builtin_amdgcn_exp2f(a0[r]); a1[r] = __builtin_amdgcn_exp2f(a1[r]); sacc = fadd_s(sacc, a0[r]); sacc2 = fadd_s(sacc2, a1[r]); }
;     pp.w[0] = ATT_PACK4(a0, 0, cvtpk); pp.w[1] = ATT_PACK4(a0, 8, cvtpk); pp.w[2] = ATT_PACK4(a1, 0, cvtpk); pp.w[3] = ATT_PACK4(a1, 8, cvtpk);
; #pragma unroll
;     for (int r = 0; r < 16; ++r) { b0[r] = __builtin_amdgcn_exp2f(b0[r]); b1[r] = __builtin_amdgcn_exp2f(b1[r]); sacc = fadd_s(sacc, b0[r]); sacc2 = fadd_s(sacc2, b1[r]); }
;     pp.w[4] = ATT_PACK4(b0, 0, cvtpk); pp.w[5] = ATT_PACK4(b0, 8, cvtpk); pp.w[6] = ATT_PACK4(b1, 0, cvtpk); pp.w[7] = ATT_PACK4(b1, 8, cvtpk);
;     const float ts = fadd_s(sacc, sacc2);
;     if (!careful && __any(!(ts < FOX_BIG))) return false;
;     st.l = fadd_s(st.l, ts);
;     return true;
; }
; __device__ __forceinline__ void fox_pair_pv(FoxState& st, const PairP& pp, lds_cptr vpB) {
;     { VFrags vf; vfrags(vf, vpB + 8192); pv(st.o, vf, pp.w[0], pp.w[1], pp.w[2], pp.w[3]); }
;     { VFrags vf; vfrags(vf, vpB); pv(st.o, vf, pp.w[4], pp.w[5], pp.w[6], pp.w[7]); }
; }
.LBB0_993:
	v_cvt_pk_bf16_f32 v152, v84, v100
	v_cvt_pk_bf16_f32 v153, v101, v102
	v_cvt_pk_bf16_f32 v154, v103, v104
	v_cvt_pk_bf16_f32 v155, v105, v106
	v_cvt_pk_bf16_f32 v148, v107, v108
	v_cvt_pk_bf16_f32 v149, v109, v110
	v_cvt_pk_bf16_f32 v150, v111, v112
	v_cvt_pk_bf16_f32 v151, v113, v114
	v_cvt_pk_bf16_f32 v144, v3, v4
	v_cvt_pk_bf16_f32 v145, v85, v86
	v_cvt_pk_bf16_f32 v146, v87, v88
	v_cvt_pk_bf16_f32 v147, v89, v90
	v_cvt_pk_bf16_f32 v140, v91, v92
	v_cvt_pk_bf16_f32 v141, v93, v94
	v_cvt_pk_bf16_f32 v142, v95, v96
	v_cvt_pk_bf16_f32 v143, v97, v98
	v_cvt_pk_bf16_f32 v136, v99, v68
	v_cvt_pk_bf16_f32 v137, v69, v70
	v_cvt_pk_bf16_f32 v138, v71, v72
	v_cvt_pk_bf16_f32 v139, v73, v74
	v_cvt_pk_bf16_f32 v132, v75, v76
	v_cvt_pk_bf16_f32 v133, v77, v78
	v_cvt_pk_bf16_f32 v134, v79, v80
	v_cvt_pk_bf16_f32 v135, v81, v82
	v_cvt_pk_bf16_f32 v128, v52, v53
	v_cvt_pk_bf16_f32 v129, v54, v55
	v_cvt_pk_bf16_f32 v130, v56, v57
	v_cvt_pk_bf16_f32 v131, v58, v59
	v_cvt_pk_bf16_f32 v124, v60, v61
	v_cvt_pk_bf16_f32 v125, v62, v63
	v_cvt_pk_bf16_f32 v126, v64, v65
	v_cvt_pk_bf16_f32 v127, v66, v67
	s_andn2_b64 vcc, exec, s[90:91]
	s_mov_b64 s[2:3], -1
	s_cbranch_vccnz .LBB0_996
	ds_read_b64_tr_b16 v[84:85], v190 offset:57344
	ds_read_b64_tr_b16 v[86:87], v190 offset:57856
	ds_read_b64_tr_b16 v[88:89], v190 offset:61440
	ds_read_b64_tr_b16 v[90:91], v190 offset:61952
	ds_read_b64_tr_b16 v[92:93], v190 offset:58368
	ds_read_b64_tr_b16 v[94:95], v190 offset:58880
	ds_read_b64_tr_b16 v[96:97], v190 offset:62464
	ds_read_b64_tr_b16 v[98:99], v190 offset:62976
	ds_read_b64_tr_b16 v[100:101], v190 offset:59392
	ds_read_b64_tr_b16 v[102:103], v190 offset:59904
	ds_read_b64_tr_b16 v[104:105], v190 offset:63488
	ds_read_b64_tr_b16 v[106:107], v190 offset:64000
	ds_read_b64_tr_b16 v[108:109], v190 offset:60416
	ds_read_b64_tr_b16 v[110:111], v190 offset:60928
	s_mov_b64 s[2:3], 0
	s_waitcnt lgkmcnt(12)
	v_mfma_f32_32x32x16_bf16 v[20:35], v[152:155], v[84:87], v[20:35]
	ds_read_b64_tr_b16 v[112:113], v190 offset:64512
	ds_read_b64_tr_b16 v[114:115], v190 offset:65024
	s_waitcnt lgkmcnt(12)
	v_mfma_f32_32x32x16_bf16 v[36:51], v[152:155], v[88:91], v[36:51]
	ds_read_b64_tr_b16 v[84:85], v190 offset:49152
	ds_read_b64_tr_b16 v[86:87], v190 offset:49664
	s_waitcnt lgkmcnt(12)
	v_mfma_f32_32x32x16_bf16 v[20:35], v[148:151], v[92:95], v[20:35]
	ds_read_b64_tr_b16 v[88:89], v190 offset:53248
	ds_read_b64_tr_b16 v[90:91], v190 offset:53760
	s_waitcnt lgkmcnt(12)
	v_mfma_f32_32x32x16_bf16 v[36:51], v[148:151], v[96:99], v[36:51]
	ds_read_b64_tr_b16 v[92:93], v190 offset:50176
	ds_read_b64_tr_b16 v[94:95], v190 offset:50688
	s_waitcnt lgkmcnt(12)
	v_mfma_f32_32x32x16_bf16 v[20:35], v[144:147], v[100:103], v[20:35]
	ds_read_b64_tr_b16 v[96:97], v190 offset:54272
	ds_read_b64_tr_b16 v[98:99], v190 offset:54784
	s_waitcnt lgkmcnt(12)
	v_mfma_f32_32x32x16_bf16 v[36:51], v[144:147], v[104:107], v[36:51]
	ds_read_b64_tr_b16 v[100:101], v190 offset:51200
	ds_read_b64_tr_b16 v[102:103], v190 offset:51712
	s_waitcnt lgkmcnt(12)
	v_mfma_f32_32x32x16_bf16 v[20:35], v[140:143], v[108:111], v[20:35]
	ds_read_b64_tr_b16 v[104:105], v190 offset:55296
	ds_read_b64_tr_b16 v[106:107], v190 offset:55808
	s_waitcnt lgkmcnt(12)
	v_mfma_f32_32x32x16_bf16 v[36:51], v[140:143], v[112:115], v[36:51]
	ds_read_b64_tr_b16 v[108:109], v190 offset:52224
	ds_read_b64_tr_b16 v[110:111], v190 offset:52736
	s_waitcnt lgkmcnt(12)
	v_mfma_f32_32x32x16_bf16 v[20:35], v[136:139], v[84:87], v[20:35]
	ds_read_b64_tr_b16 v[112:113], v190 offset:56320
	ds_read_b64_tr_b16 v[114:115], v190 offset:56832
	s_waitcnt lgkmcnt(12)
	v_mfma_f32_32x32x16_bf16 v[36:51], v[136:139], v[88:91], v[36:51]
	s_waitcnt lgkmcnt(10)
	v_mfma_f32_32x32x16_bf16 v[20:35], v[132:135], v[92:95], v[20:35]
	s_waitcnt lgkmcnt(8)
	v_mfma_f32_32x32x16_bf16 v[36:51], v[132:135], v[96:99], v[36:51]
	s_waitcnt lgkmcnt(6)
	v_mfma_f32_32x32x16_bf16 v[20:35], v[128:131], v[100:103], v[20:35]
	s_waitcnt lgkmcnt(4)
	v_mfma_f32_32x32x16_bf16 v[36:51], v[128:131], v[104:107], v[36:51]
	s_waitcnt lgkmcnt(2)
	v_mfma_f32_32x32x16_bf16 v[20:35], v[124:127], v[108:111], v[20:35]
	s_waitcnt lgkmcnt(0)
	v_mfma_f32_32x32x16_bf16 v[36:51], v[124:127], v[112:115], v[36:51]
	s_branch .LBB0_997
